# attention: double-buffered K/V LDS tiles with one barrier per key tile, V tile read as b128 (keys permuted in LDS), sc1 write-through on 16-byte stores
# speedup vs baseline: 1.0562x; 1.0158x over previous
.LBB0_20:
	ds_write_b128 v21, v[4:7]
	s_waitcnt lgkmcnt(0)
	s_barrier
	s_waitcnt vmcnt(0)
	ds_read2st64_b32 v[0:1], v16 offset1:1
	ds_read2st64_b32 v[2:3], v16 offset0:2 offset1:3
	ds_read2st64_b32 v[4:5], v16 offset0:4 offset1:5
	ds_read2st64_b32 v[6:7], v16 offset0:6 offset1:7
	v_lshl_add_u64 v[24:25], s[10:11], 1, v[12:13]
	s_waitcnt lgkmcnt(3)
	v_cvt_pk_bf16_f32 v0, v0, v1
	s_waitcnt lgkmcnt(2)
	v_cvt_pk_bf16_f32 v1, v2, v3
	s_waitcnt lgkmcnt(1)
	v_cvt_pk_bf16_f32 v2, v4, v5
	v_or_b32_e32 v4, s22, v8
	v_ashrrev_i32_e32 v5, 31, v4
	s_waitcnt lgkmcnt(0)
	v_cvt_pk_bf16_f32 v3, v6, v7
	v_lshlrev_b64 v[4:5], 11, v[4:5]
	ds_read2st64_b32 v[6:7], v22 offset1:1
	ds_read2st64_b32 v[26:27], v22 offset0:2 offset1:3
	ds_read2st64_b32 v[28:29], v22 offset0:4 offset1:5
	ds_read2st64_b32 v[30:31], v22 offset0:6 offset1:7
	v_lshl_add_u64 v[4:5], v[24:25], 0, v[4:5]
	global_store_dwordx4 v[4:5], v[0:3], off sc1
	v_add_u32_e32 v4, s22, v18
	v_ashrrev_i32_e32 v5, 31, v4
	v_lshlrev_b64 v[4:5], 11, v[4:5]
	s_add_i32 s19, s19, s82
	s_add_i32 s3, s3, s16
	s_waitcnt lgkmcnt(3)
	v_cvt_pk_bf16_f32 v0, v6, v7
	s_waitcnt lgkmcnt(2)
	v_cvt_pk_bf16_f32 v1, v26, v27
	s_waitcnt lgkmcnt(1)
	v_cvt_pk_bf16_f32 v2, v28, v29
	s_waitcnt lgkmcnt(0)
	v_cvt_pk_bf16_f32 v3, v30, v31
	v_lshl_add_u64 v[4:5], v[24:25], 0, v[4:5]
	s_cmpk_lt_i32 s19, 0x300
	v_add_u32_e32 v23, s17, v23
	global_store_dwordx4 v[4:5], v[0:3], off sc1
	s_cbranch_scc0 .LBB0_39

.LBB0_41:
	s_waitcnt vmcnt(1)
	ds_write_b128 v18, v[4:7]
	s_waitcnt vmcnt(0)
	ds_write_b128 v19, v[0:3]
	s_waitcnt lgkmcnt(0)
	s_barrier
	ds_read2st64_b32 v[0:1], v14 offset1:1
	ds_read2st64_b32 v[2:3], v14 offset0:2 offset1:3
	ds_read2st64_b32 v[4:5], v14 offset0:4 offset1:5
	ds_read2st64_b32 v[6:7], v14 offset0:6 offset1:7
	s_add_i32 s6, s3, s10
	s_waitcnt lgkmcnt(3)
	v_cvt_pk_bf16_f32 v0, v0, v1
	s_waitcnt lgkmcnt(2)
	v_cvt_pk_bf16_f32 v1, v2, v3
	s_waitcnt lgkmcnt(1)
	v_cvt_pk_bf16_f32 v2, v4, v5
	v_or_b32_e32 v4, s5, v12
	s_ashr_i32 s7, s6, 31
	v_ashrrev_i32_e32 v5, 31, v4
	v_lshl_add_u64 v[22:23], s[6:7], 1, v[10:11]
	s_waitcnt lgkmcnt(0)
	v_cvt_pk_bf16_f32 v3, v6, v7
	v_lshlrev_b64 v[4:5], 12, v[4:5]
	ds_read2st64_b32 v[6:7], v20 offset1:1
	ds_read2st64_b32 v[24:25], v20 offset0:2 offset1:3
	ds_read2st64_b32 v[26:27], v20 offset0:4 offset1:5
	ds_read2st64_b32 v[28:29], v20 offset0:6 offset1:7
	v_lshl_add_u64 v[4:5], v[22:23], 0, v[4:5]
	global_store_dwordx4 v[4:5], v[0:3], off sc1
	v_add_u32_e32 v4, s5, v16
	v_ashrrev_i32_e32 v5, 31, v4
	v_lshlrev_b64 v[4:5], 12, v[4:5]
	s_add_i32 s9, s9, s82
	s_add_i32 s3, s3, s8
	s_waitcnt lgkmcnt(3)
	v_cvt_pk_bf16_f32 v0, v6, v7
	s_waitcnt lgkmcnt(2)
	v_cvt_pk_bf16_f32 v1, v24, v25
	s_waitcnt lgkmcnt(1)
	v_cvt_pk_bf16_f32 v2, v26, v27
	s_waitcnt lgkmcnt(0)
	v_cvt_pk_bf16_f32 v3, v28, v29
	v_lshl_add_u64 v[4:5], v[22:23], 0, v[4:5]
	s_cmpk_lt_i32 s9, 0x100
	global_store_dwordx4 v[4:5], v[0:3], off sc1
	s_cbranch_scc0 .LBB0_46

.LBB0_130:
	v_lshl_add_u64 v[20:21], v[0:1], 0, s[60:61]
	v_add_co_u32_e32 v22, vcc, 0x6000000, v20
	ds_read_b128 v[4:7], v2
	ds_read_b128 v[8:11], v2 offset:2304
	ds_read_b128 v[12:15], v2 offset:4608
	ds_read_b128 v[16:19], v2 offset:6912
	v_addc_co_u32_e32 v23, vcc, 0, v21, vcc
	v_add_co_u32_e32 v24, vcc, 0x6010000, v20
	s_add_u32 s60, s60, 0x40000
	s_nop 0
	v_addc_co_u32_e32 v25, vcc, 0, v21, vcc
	v_add_co_u32_e32 v26, vcc, 0x6020000, v20
	s_addc_u32 s61, s61, 0
	s_nop 0
	v_addc_co_u32_e32 v27, vcc, 0, v21, vcc
	v_add_co_u32_e32 v20, vcc, 0x6030000, v20
	v_add_u32_e32 v2, 0x2400, v2
	s_cmp_lg_u32 s60, 0x80000
	v_addc_co_u32_e32 v21, vcc, 0, v21, vcc
	s_waitcnt lgkmcnt(3)
	global_store_dwordx4 v[22:23], v[4:7], off sc1
	s_waitcnt lgkmcnt(2)
	global_store_dwordx4 v[24:25], v[8:11], off sc1
	s_waitcnt lgkmcnt(1)
	global_store_dwordx4 v[26:27], v[12:15], off sc1
	s_waitcnt lgkmcnt(0)
	global_store_dwordx4 v[20:21], v[16:19], off sc1
	s_cbranch_scc1 .LBB0_130
	s_waitcnt lgkmcnt(0)
	s_branch .LBB0_113

.LBB0_203:
	v_lshl_add_u64 v[18:19], v[168:169], 0, s[16:17]
	v_add_co_u32_e32 v20, vcc, 0x6000000, v18
	ds_read_b128 v[2:5], v0
	ds_read_b128 v[6:9], v0 offset:1152
	ds_read_b128 v[10:13], v0 offset:2304
	ds_read_b128 v[14:17], v0 offset:3456
	v_addc_co_u32_e32 v21, vcc, 0, v19, vcc
	v_add_co_u32_e32 v22, vcc, 0x6008000, v18
	s_add_u32 s16, s16, 0x20000
	s_nop 0
	v_addc_co_u32_e32 v23, vcc, 0, v19, vcc
	v_add_co_u32_e32 v24, vcc, 0x6010000, v18
	s_addc_u32 s17, s17, 0
	s_nop 0
	v_addc_co_u32_e32 v25, vcc, 0, v19, vcc
	v_add_co_u32_e32 v18, vcc, 0x6018000, v18
	v_add_u32_e32 v0, 0x1200, v0
	s_cmp_lg_u32 s16, 0x40000
	v_addc_co_u32_e32 v19, vcc, 0, v19, vcc
	s_waitcnt lgkmcnt(3)
	global_store_dwordx4 v[20:21], v[2:5], off sc1
	s_waitcnt lgkmcnt(2)
	global_store_dwordx4 v[22:23], v[6:9], off sc1
	s_waitcnt lgkmcnt(1)
	global_store_dwordx4 v[24:25], v[10:13], off sc1
	s_waitcnt lgkmcnt(0)
	global_store_dwordx4 v[18:19], v[14:17], off sc1
	s_cbranch_scc1 .LBB0_203
	s_waitcnt lgkmcnt(0)
	s_add_i32 s42, s42, s82
	s_add_i32 s41, s41, s82
	s_cmpk_lt_i32 s42, 0x400
	s_cbranch_scc1 .LBB0_190

.LBB0_326:
	ds_write_b128 v22, v[4:7]
	s_waitcnt lgkmcnt(0)
	s_barrier
	s_waitcnt vmcnt(0)
	ds_read2st64_b32 v[0:1], v17 offset1:1
	ds_read2st64_b32 v[2:3], v17 offset0:2 offset1:3
	ds_read2st64_b32 v[4:5], v17 offset0:4 offset1:5
	ds_read2st64_b32 v[6:7], v17 offset0:6 offset1:7
	v_lshl_add_u64 v[24:25], s[10:11], 1, v[14:15]
	s_waitcnt lgkmcnt(3)
	v_cvt_pk_bf16_f32 v0, v0, v1
	s_waitcnt lgkmcnt(2)
	v_cvt_pk_bf16_f32 v1, v2, v3
	s_waitcnt lgkmcnt(1)
	v_cvt_pk_bf16_f32 v2, v4, v5
	v_or_b32_e32 v4, s17, v8
	v_ashrrev_i32_e32 v5, 31, v4
	s_waitcnt lgkmcnt(0)
	v_cvt_pk_bf16_f32 v3, v6, v7
	v_lshlrev_b64 v[4:5], 11, v[4:5]
	ds_read2st64_b32 v[6:7], v23 offset1:1
	ds_read2st64_b32 v[26:27], v23 offset0:2 offset1:3
	ds_read2st64_b32 v[28:29], v23 offset0:4 offset1:5
	ds_read2st64_b32 v[30:31], v23 offset0:6 offset1:7
	v_lshl_add_u64 v[4:5], v[24:25], 0, v[4:5]
	global_store_dwordx4 v[4:5], v[0:3], off sc1
	v_add_u32_e32 v4, s17, v19
	v_ashrrev_i32_e32 v5, 31, v4
	v_lshlrev_b64 v[4:5], 11, v[4:5]
	s_add_i32 s16, s16, s82
	s_add_i32 s15, s15, s14
	s_waitcnt lgkmcnt(3)
	v_cvt_pk_bf16_f32 v0, v6, v7
	s_waitcnt lgkmcnt(2)
	v_cvt_pk_bf16_f32 v1, v26, v27
	s_waitcnt lgkmcnt(1)
	v_cvt_pk_bf16_f32 v2, v28, v29
	s_waitcnt lgkmcnt(0)
	v_cvt_pk_bf16_f32 v3, v30, v31
	v_lshl_add_u64 v[4:5], v[24:25], 0, v[4:5]
	s_cmpk_lt_i32 s16, 0x200
	global_store_dwordx4 v[4:5], v[0:3], off sc1
	s_cbranch_scc0 .LBB0_345

.LBB0_346:
	s_waitcnt vmcnt(1)
	ds_write_b128 v21, v[4:7]
	s_waitcnt vmcnt(0)
	ds_write_b128 v22, v[0:3]
	s_waitcnt lgkmcnt(0)
	s_barrier
	ds_read2st64_b32 v[0:1], v17 offset1:1
	ds_read2st64_b32 v[2:3], v17 offset0:2 offset1:3
	ds_read2st64_b32 v[4:5], v17 offset0:4 offset1:5
	ds_read2st64_b32 v[6:7], v17 offset0:6 offset1:7
	s_add_i32 s6, s3, s9
	s_waitcnt lgkmcnt(3)
	v_cvt_pk_bf16_f32 v0, v0, v1
	s_waitcnt lgkmcnt(2)
	v_cvt_pk_bf16_f32 v1, v2, v3
	s_waitcnt lgkmcnt(1)
	v_cvt_pk_bf16_f32 v2, v4, v5
	v_or_b32_e32 v4, s5, v8
	s_ashr_i32 s7, s6, 31
	v_ashrrev_i32_e32 v5, 31, v4
	v_lshl_add_u64 v[14:15], s[6:7], 1, v[12:13]
	s_waitcnt lgkmcnt(0)
	v_cvt_pk_bf16_f32 v3, v6, v7
	v_lshlrev_b64 v[4:5], 12, v[4:5]
	ds_read2st64_b32 v[6:7], v23 offset1:1
	ds_read2st64_b32 v[24:25], v23 offset0:2 offset1:3
	ds_read2st64_b32 v[26:27], v23 offset0:4 offset1:5
	ds_read2st64_b32 v[28:29], v23 offset0:6 offset1:7
	v_lshl_add_u64 v[4:5], v[14:15], 0, v[4:5]
	global_store_dwordx4 v[4:5], v[0:3], off sc1
	v_add_u32_e32 v4, s5, v19
	v_ashrrev_i32_e32 v5, 31, v4
	v_lshlrev_b64 v[4:5], 12, v[4:5]
	s_add_i32 s8, s8, s82
	s_add_i32 s3, s3, s14
	s_waitcnt lgkmcnt(3)
	v_cvt_pk_bf16_f32 v0, v6, v7
	s_waitcnt lgkmcnt(2)
	v_cvt_pk_bf16_f32 v1, v24, v25
	s_waitcnt lgkmcnt(1)
	v_cvt_pk_bf16_f32 v2, v26, v27
	s_waitcnt lgkmcnt(0)
	v_cvt_pk_bf16_f32 v3, v28, v29
	v_lshl_add_u64 v[4:5], v[14:15], 0, v[4:5]
	s_cmpk_lt_i32 s8, 0x200
	global_store_dwordx4 v[4:5], v[0:3], off sc1
	s_cbranch_scc0 .LBB0_351

.LBB0_353:
	s_waitcnt vmcnt(1)
	ds_write_b128 v18, v[4:7]
	s_waitcnt vmcnt(0)
	ds_write_b128 v19, v[0:3]
	s_waitcnt lgkmcnt(0)
	s_barrier
	ds_read2st64_b32 v[0:1], v14 offset1:1
	ds_read2st64_b32 v[2:3], v14 offset0:2 offset1:3
	ds_read2st64_b32 v[4:5], v14 offset0:4 offset1:5
	ds_read2st64_b32 v[6:7], v14 offset0:6 offset1:7
	s_add_i32 s6, s3, s14
	s_waitcnt lgkmcnt(3)
	v_cvt_pk_bf16_f32 v0, v0, v1
	s_waitcnt lgkmcnt(2)
	v_cvt_pk_bf16_f32 v1, v2, v3
	s_waitcnt lgkmcnt(1)
	v_cvt_pk_bf16_f32 v2, v4, v5
	v_or_b32_e32 v4, s5, v12
	s_ashr_i32 s7, s6, 31
	v_ashrrev_i32_e32 v5, 31, v4
	v_lshl_add_u64 v[22:23], s[6:7], 1, v[10:11]
	s_waitcnt lgkmcnt(0)
	v_cvt_pk_bf16_f32 v3, v6, v7
	v_lshlrev_b64 v[4:5], 12, v[4:5]
	ds_read2st64_b32 v[6:7], v20 offset1:1
	ds_read2st64_b32 v[24:25], v20 offset0:2 offset1:3
	ds_read2st64_b32 v[26:27], v20 offset0:4 offset1:5
	ds_read2st64_b32 v[28:29], v20 offset0:6 offset1:7
	v_lshl_add_u64 v[4:5], v[22:23], 0, v[4:5]
	global_store_dwordx4 v[4:5], v[0:3], off sc1
	v_add_u32_e32 v4, s5, v16
	v_ashrrev_i32_e32 v5, 31, v4
	v_lshlrev_b64 v[4:5], 12, v[4:5]
	s_add_i32 s11, s11, s82
	s_add_i32 s3, s3, s10
	s_waitcnt lgkmcnt(3)
	v_cvt_pk_bf16_f32 v0, v6, v7
	s_waitcnt lgkmcnt(2)
	v_cvt_pk_bf16_f32 v1, v24, v25
	s_waitcnt lgkmcnt(1)
	v_cvt_pk_bf16_f32 v2, v26, v27
	s_waitcnt lgkmcnt(0)
	v_cvt_pk_bf16_f32 v3, v28, v29
	v_lshl_add_u64 v[4:5], v[22:23], 0, v[4:5]
	s_cmpk_lt_i32 s11, 0x100
	global_store_dwordx4 v[4:5], v[0:3], off sc1
	s_cbranch_scc0 .LBB0_358

.LBB0_459:
	v_add_u32_e32 v14, s46, v139
	ds_read_b128 v[2:5], v14
	ds_read_b128 v[6:9], v14 offset:1024
	ds_read_b128 v[10:13], v14 offset:2048
	ds_read_b128 v[14:17], v14 offset:3072
	s_addk_i32 s46, 0x1000
	s_cmpk_eq_i32 s46, 0x4000
	s_waitcnt lgkmcnt(3)
	global_store_dwordx4 v[0:1], v[2:5], off offset:-2048 sc1
	s_waitcnt lgkmcnt(2)
	global_store_dwordx4 v[0:1], v[6:9], off offset:-1024 sc1
	s_waitcnt lgkmcnt(1)
	global_store_dwordx4 v[0:1], v[10:13], off sc1
	s_waitcnt lgkmcnt(0)
	global_store_dwordx4 v[0:1], v[14:17], off offset:1024 sc1
	v_lshl_add_u64 v[0:1], v[0:1], 0, s[44:45]
	s_cbranch_scc0 .LBB0_459
	s_waitcnt lgkmcnt(0)
	s_add_i32 s60, s60, s82
	s_add_i32 s55, s55, s82
	s_cmpk_gt_i32 s60, 0x1ff
	s_cbranch_scc0 .LBB0_452

.LBB0_667:
	ds_read_b128 v[2:5], v0
	v_lshl_add_u64 v[6:7], v[138:139], 0, s[68:69]
	v_add_co_u32_e32 v8, vcc, 0x6000000, v6
	s_add_u32 s68, s68, 0x20000
	s_nop 0
	v_addc_co_u32_e32 v9, vcc, 0, v7, vcc
	s_waitcnt lgkmcnt(0)
	global_store_dwordx4 v[8:9], v[2:5], off sc1
	ds_read_b128 v[2:5], v0 offset:1152
	v_add_co_u32_e32 v8, vcc, 0x6008000, v6
	s_addc_u32 s69, s69, 0
	s_nop 0
	v_addc_co_u32_e32 v9, vcc, 0, v7, vcc
	s_waitcnt lgkmcnt(0)
	global_store_dwordx4 v[8:9], v[2:5], off sc1
	ds_read_b128 v[2:5], v0 offset:2304
	v_add_co_u32_e32 v8, vcc, 0x6010000, v6
	s_cmp_lg_u32 s68, 0x80000
	s_nop 0
	v_addc_co_u32_e32 v9, vcc, 0, v7, vcc
	s_waitcnt lgkmcnt(0)
	global_store_dwordx4 v[8:9], v[2:5], off sc1
	ds_read_b128 v[2:5], v0 offset:3456
	v_add_co_u32_e32 v6, vcc, 0x6018000, v6
	v_add_u32_e32 v0, 0x1200, v0
	s_nop 0
	v_addc_co_u32_e32 v7, vcc, 0, v7, vcc
	s_waitcnt lgkmcnt(0)
	global_store_dwordx4 v[6:7], v[2:5], off sc1
	s_cbranch_scc1 .LBB0_667
	v_mov_b32_e32 v6, v181
	s_waitcnt lgkmcnt(0)
	s_lshl_b32 s68, s6, 20
	v_lshrrev_b32_e32 v7, 4, v6
	v_lshlrev_b32_e32 v1, 6, v6
	v_xor_b32_e32 v0, v7, v6
	v_and_b32_e32 v8, 0x3c0, v1
	v_lshlrev_b32_e32 v1, 8, v6
	v_lshlrev_b32_e32 v0, 3, v0
	v_and_b32_e32 v1, 0xfffff800, v1
	s_lshl_b64 s[20:21], s[64:65], 20
	v_and_or_b32 v0, v0, 56, v1
	s_add_u32 s20, s75, s20
	v_ashrrev_i32_e32 v1, 31, v0
	s_addc_u32 s21, s88, s21
	v_lshlrev_b64 v[0:1], 1, v[0:1]
	v_lshl_add_u32 v174, v6, 4, 0
	v_lshl_add_u64 v[2:3], s[20:21], 0, v[0:1]
	v_readfirstlane_b32 s20, v174
	v_add_u32_e32 v9, 0x2000, v174
	s_mov_b32 m0, s20
	v_readfirstlane_b32 s20, v9
	v_add_u32_e32 v9, 0x4000, v174
	s_barrier
	global_load_lds_dwordx4 v[2:3], off
	v_lshl_add_u64 v[4:5], v[2:3], 0, s[10:11]
	s_mov_b32 m0, s20
	v_readfirstlane_b32 s20, v9
	global_load_lds_dwordx4 v[4:5], off
	v_lshl_add_u64 v[4:5], v[2:3], 0, s[40:41]
	s_mov_b32 m0, s20
	s_lshl_b32 s64, s95, 12
	global_load_lds_dwordx4 v[4:5], off
	v_add_u32_e32 v4, 0x6000, v174
	s_add_u32 s64, s89, s64
	v_readfirstlane_b32 s20, v4
	v_add_u32_e32 v4, 0x8000, v174
	s_addc_u32 s65, s90, 0
	v_lshl_add_u64 v[2:3], v[2:3], 0, s[42:43]
	s_mov_b32 m0, s20
	v_readfirstlane_b32 s20, v4
	v_add_u32_e32 v9, 0xa000, v174
	global_load_lds_dwordx4 v[2:3], off
	v_lshl_add_u64 v[2:3], s[64:65], 0, v[0:1]
	s_mov_b32 m0, s20
	v_readfirstlane_b32 s20, v9
	v_add_u32_e32 v9, 0xc000, v174
	global_load_lds_dwordx4 v[2:3], off
	v_lshl_add_u64 v[4:5], v[2:3], 0, s[10:11]
	s_mov_b32 m0, s20
	v_readfirstlane_b32 s20, v9
	global_load_lds_dwordx4 v[4:5], off
	v_lshl_add_u64 v[4:5], v[2:3], 0, s[40:41]
	s_mov_b32 m0, s20
	v_lshl_add_u64 v[2:3], v[2:3], 0, s[42:43]
	global_load_lds_dwordx4 v[4:5], off
	v_add_u32_e32 v4, 0xe000, v174
	s_mov_b32 s69, 0
	v_readfirstlane_b32 s20, v4
	s_mov_b32 m0, s20
	v_ashrrev_i32_e32 v4, 6, v6
	global_load_lds_dwordx4 v[2:3], off
	v_lshrrev_b32_e32 v5, 30, v4
	v_add_u32_e32 v5, v4, v5
	s_lshl_b64 s[20:21], s[66:67], 20
	v_bfe_u32 v2, v6, 4, 2
	v_bfe_u32 v3, v6, 1, 3
	v_and_b32_e32 v6, 0x7fffc, v5
	s_add_u32 s20, s34, s20
	v_sub_u32_e32 v4, v4, v6
	s_addc_u32 s21, s35, s21
	v_lshlrev_b32_e32 v5, 12, v5
	v_lshlrev_b32_e32 v176, 13, v4
	v_bitop3_b32 v4, v7, v3, 3 bitop3:0x6c
	v_bitop3_b32 v2, v2, v3, 4 bitop3:0x36
	v_lshl_add_u64 v[142:143], s[20:21], 0, v[0:1]
	s_add_u32 s20, s34, s68
	v_and_b32_e32 v175, 0xffffc000, v5
	v_lshlrev_b32_e32 v5, 3, v4
	v_lshlrev_b32_e32 v2, 3, v2
	s_addc_u32 s21, s35, 0
	v_mov_b32_e32 v4, 0
	v_lshl_add_u64 v[144:145], s[20:21], 0, v[0:1]
	s_mov_b64 s[64:65], 0
	v_lshlrev_b32_e32 v177, 1, v8
	v_lshlrev_b32_e32 v178, 1, v5
	v_lshlrev_b32_e32 v179, 1, v2
	s_mov_b32 s68, 0
	v_mov_b32_e32 v5, v4
	v_mov_b32_e32 v6, v4
	v_mov_b32_e32 v7, v4
	v_mov_b32_e32 v8, v4
	v_mov_b32_e32 v9, v4
	v_mov_b32_e32 v10, v4
	v_mov_b32_e32 v11, v4
	v_mov_b32_e32 v0, v4
	v_mov_b32_e32 v1, v4
	v_mov_b32_e32 v2, v4
	v_mov_b32_e32 v3, v4
	v_mov_b32_e32 v12, v4
	v_mov_b32_e32 v13, v4
	v_mov_b32_e32 v14, v4
	v_mov_b32_e32 v15, v4
	v_mov_b32_e32 v16, v4
	v_mov_b32_e32 v17, v4
	v_mov_b32_e32 v18, v4
	v_mov_b32_e32 v19, v4
	v_mov_b32_e32 v20, v4
	v_mov_b32_e32 v21, v4
	v_mov_b32_e32 v22, v4
	v_mov_b32_e32 v23, v4
	v_mov_b32_e32 v24, v4
	v_mov_b32_e32 v25, v4
	v_mov_b32_e32 v26, v4
	v_mov_b32_e32 v27, v4
	v_mov_b32_e32 v28, v4
	v_mov_b32_e32 v29, v4
	v_mov_b32_e32 v30, v4
	v_mov_b32_e32 v31, v4
	v_mov_b32_e32 v32, v4
	v_mov_b32_e32 v33, v4
	v_mov_b32_e32 v34, v4
	v_mov_b32_e32 v35, v4
	v_mov_b32_e32 v36, v4
	v_mov_b32_e32 v37, v4
	v_mov_b32_e32 v38, v4
	v_mov_b32_e32 v39, v4
	v_mov_b32_e32 v40, v4
	v_mov_b32_e32 v41, v4
	v_mov_b32_e32 v42, v4
	v_mov_b32_e32 v43, v4
	v_mov_b32_e32 v44, v4
	v_mov_b32_e32 v45, v4
	v_mov_b32_e32 v46, v4
	v_mov_b32_e32 v47, v4
	v_mov_b32_e32 v48, v4
	v_mov_b32_e32 v49, v4
	v_mov_b32_e32 v50, v4
	v_mov_b32_e32 v51, v4
	v_mov_b32_e32 v52, v4
	v_mov_b32_e32 v53, v4
	v_mov_b32_e32 v54, v4
	v_mov_b32_e32 v55, v4
	v_mov_b32_e32 v56, v4
	v_mov_b32_e32 v57, v4
	v_mov_b32_e32 v58, v4
	v_mov_b32_e32 v59, v4
	v_mov_b32_e32 v60, v4
	v_mov_b32_e32 v61, v4
	v_mov_b32_e32 v62, v4
	v_mov_b32_e32 v63, v4
	v_mov_b32_e32 v64, v4
	v_mov_b32_e32 v65, v4
	v_mov_b32_e32 v66, v4
	v_mov_b32_e32 v67, v4
	v_mov_b32_e32 v68, v4
	v_mov_b32_e32 v69, v4
	v_mov_b32_e32 v70, v4
	v_mov_b32_e32 v71, v4
	v_mov_b32_e32 v72, v4
	v_mov_b32_e32 v73, v4
	v_mov_b32_e32 v74, v4
	v_mov_b32_e32 v75, v4
	v_mov_b32_e32 v76, v4
	v_mov_b32_e32 v77, v4
	v_mov_b32_e32 v78, v4
	v_mov_b32_e32 v79, v4
	v_mov_b32_e32 v80, v4
	v_mov_b32_e32 v81, v4
	v_mov_b32_e32 v82, v4
	v_mov_b32_e32 v83, v4
	v_mov_b32_e32 v84, v4
	v_mov_b32_e32 v85, v4
	v_mov_b32_e32 v86, v4
	v_mov_b32_e32 v87, v4
	v_mov_b32_e32 v88, v4
	v_mov_b32_e32 v89, v4
	v_mov_b32_e32 v90, v4
	v_mov_b32_e32 v91, v4
	v_mov_b32_e32 v92, v4
	v_mov_b32_e32 v93, v4
	v_mov_b32_e32 v94, v4
	v_mov_b32_e32 v95, v4
	v_mov_b32_e32 v96, v4
	v_mov_b32_e32 v97, v4
	v_mov_b32_e32 v98, v4
	v_mov_b32_e32 v99, v4
	v_mov_b32_e32 v100, v4
	v_mov_b32_e32 v101, v4
	v_mov_b32_e32 v102, v4
	v_mov_b32_e32 v103, v4
	v_mov_b32_e32 v104, v4
	v_mov_b32_e32 v105, v4
	v_mov_b32_e32 v106, v4
	v_mov_b32_e32 v107, v4
	v_mov_b32_e32 v108, v4
	v_mov_b32_e32 v109, v4
	v_mov_b32_e32 v110, v4
	v_mov_b32_e32 v111, v4
	v_mov_b32_e32 v112, v4
	v_mov_b32_e32 v113, v4
	v_mov_b32_e32 v114, v4
	v_mov_b32_e32 v115, v4
	v_mov_b32_e32 v116, v4
	v_mov_b32_e32 v117, v4
	v_mov_b32_e32 v118, v4
	v_mov_b32_e32 v119, v4
	v_mov_b32_e32 v120, v4
	v_mov_b32_e32 v121, v4
	v_mov_b32_e32 v122, v4
	v_mov_b32_e32 v123, v4
	v_mov_b32_e32 v124, v4
	v_mov_b32_e32 v125, v4
	v_mov_b32_e32 v126, v4
	v_mov_b32_e32 v127, v4
	s_waitcnt vmcnt(0) lgkmcnt(0)
	s_barrier
	v_add3_u32 v180, v175, v177, v178
	v_add3_u32 v249, v176, v177, v178
	v_add3_u32 v248, v175, v177, v179
	v_add3_u32 v250, v176, v177, v179
	v_readfirstlane_b32 s69, v174
	ds_read_b128 v[182:185], v180
	ds_read_b128 v[186:189], v180 offset:2048
	ds_read_b128 v[190:193], v180 offset:4096
	ds_read_b128 v[194:197], v180 offset:6144
	ds_read_b128 v[214:217], v249 offset:32768
	ds_read_b128 v[218:221], v249 offset:34816
	ds_read_b128 v[222:225], v249 offset:36864
	ds_read_b128 v[226:229], v249 offset:38912
	s_mov_b32 s68, 0
	s_mov_b64 s[64:65], 0
	s_add_u32 s69, s69, 0x10000
	s_add_u32 s66, s64, s44
	s_addc_u32 s67, s65, s45
	s_mov_b32 m0, s69
	v_lshl_add_u64 v[246:247], v[142:143], 0, s[66:67]
	global_load_lds_dwordx4 v[246:247], off
	s_add_u32 s66, s64, s46
	s_addc_u32 s67, s65, s47
	s_add_u32 m0, s69, 0x2000
	v_lshl_add_u64 v[246:247], v[142:143], 0, s[66:67]
	global_load_lds_dwordx4 v[246:247], off
	s_add_u32 s66, s64, s48
	s_addc_u32 s67, s65, s49
	s_add_u32 m0, s69, 0x4000
	v_lshl_add_u64 v[246:247], v[142:143], 0, s[66:67]
	global_load_lds_dwordx4 v[246:247], off
	s_add_u32 s66, s64, s50
	s_addc_u32 s67, s65, s51
	s_add_u32 m0, s69, 0x6000
	v_lshl_add_u64 v[246:247], v[142:143], 0, s[66:67]
	global_load_lds_dwordx4 v[246:247], off
	s_add_u32 s66, s64, s52
	s_addc_u32 s67, s65, s53
	s_add_u32 m0, s69, 0x8000
	v_lshl_add_u64 v[246:247], v[144:145], 0, s[66:67]
	global_load_lds_dwordx4 v[246:247], off
	s_add_u32 s66, s64, s54
	s_addc_u32 s67, s65, s55
	s_add_u32 m0, s69, 0xa000
	v_lshl_add_u64 v[246:247], v[144:145], 0, s[66:67]
	global_load_lds_dwordx4 v[246:247], off
	s_add_u32 s66, s64, s60
	s_addc_u32 s67, s65, s61
	s_add_u32 m0, s69, 0xc000
	v_lshl_add_u64 v[246:247], v[144:145], 0, s[66:67]
	global_load_lds_dwordx4 v[246:247], off
	s_add_u32 s66, s64, s62
	s_addc_u32 s67, s65, s63
	s_add_u32 m0, s69, 0xe000
	v_lshl_add_u64 v[246:247], v[144:145], 0, s[66:67]
	global_load_lds_dwordx4 v[246:247], off
	s_branch .Lg6_entry

.LBB0_679:
	v_lshl_add_u64 v[82:83], v[140:141], 0, s[64:65]
	v_add_co_u32_e32 v84, vcc, 0x6000000, v82
	ds_read_b128 v[66:69], v64
	ds_read_b128 v[70:73], v64 offset:1152
	ds_read_b128 v[74:77], v64 offset:2304
	ds_read_b128 v[78:81], v64 offset:3456
	v_addc_co_u32_e32 v85, vcc, 0, v83, vcc
	v_add_co_u32_e32 v86, vcc, 0x6008000, v82
	s_add_u32 s64, s64, 0x20000
	s_nop 0
	v_addc_co_u32_e32 v87, vcc, 0, v83, vcc
	v_add_co_u32_e32 v88, vcc, 0x6010000, v82
	s_addc_u32 s65, s65, 0
	s_nop 0
	v_addc_co_u32_e32 v89, vcc, 0, v83, vcc
	v_add_co_u32_e32 v82, vcc, 0x6018000, v82
	v_add_u32_e32 v64, 0x1200, v64
	s_cmp_lg_u32 s64, 0x40000
	v_addc_co_u32_e32 v83, vcc, 0, v83, vcc
	s_waitcnt lgkmcnt(3)
	global_store_dwordx4 v[84:85], v[66:69], off sc1
	s_waitcnt lgkmcnt(2)
	global_store_dwordx4 v[86:87], v[70:73], off sc1
	s_waitcnt lgkmcnt(1)
	global_store_dwordx4 v[88:89], v[74:77], off sc1
	s_waitcnt lgkmcnt(0)
	global_store_dwordx4 v[82:83], v[78:81], off sc1
	s_cbranch_scc1 .LBB0_679
	s_waitcnt lgkmcnt(0)
	s_mov_b64 s[64:65], 0
	v_mov_b32_e32 v64, v171

.LBB0_685:
	v_lshl_add_u64 v[18:19], v[138:139], 0, s[64:65]
	v_add_co_u32_e32 v20, vcc, 0x6040000, v18
	ds_read_b128 v[2:5], v0
	ds_read_b128 v[6:9], v0 offset:1152
	ds_read_b128 v[10:13], v0 offset:2304
	ds_read_b128 v[14:17], v0 offset:3456
	v_addc_co_u32_e32 v21, vcc, 0, v19, vcc
	v_add_co_u32_e32 v22, vcc, 0x6048000, v18
	s_add_u32 s64, s64, 0x20000
	s_nop 0
	v_addc_co_u32_e32 v23, vcc, 0, v19, vcc
	v_add_co_u32_e32 v24, vcc, 0x6050000, v18
	s_addc_u32 s65, s65, 0
	s_nop 0
	v_addc_co_u32_e32 v25, vcc, 0, v19, vcc
	v_add_co_u32_e32 v18, vcc, 0x6058000, v18
	v_add_u32_e32 v0, 0x1200, v0
	s_cmp_lg_u32 s64, 0x40000
	v_addc_co_u32_e32 v19, vcc, 0, v19, vcc
	s_waitcnt lgkmcnt(3)
	global_store_dwordx4 v[20:21], v[2:5], off sc1
	s_waitcnt lgkmcnt(2)
	global_store_dwordx4 v[22:23], v[6:9], off sc1
	s_waitcnt lgkmcnt(1)
	global_store_dwordx4 v[24:25], v[10:13], off sc1
	s_waitcnt lgkmcnt(0)
	global_store_dwordx4 v[18:19], v[14:17], off sc1
	s_cbranch_scc1 .LBB0_685
	s_waitcnt lgkmcnt(0)
	s_add_i32 s94, s94, s82
	s_add_i32 s93, s93, s82
	s_add_i32 s91, s91, s92
	s_cmpk_lt_i32 s94, 0x200
	s_cbranch_scc1 .LBB0_660
	v_readlane_b32 s0, v252, 2
	v_readlane_b32 s1, v252, 3
	s_load_dword s92, s[0:1], 0x148
	v_readlane_b32 s94, v252, 4
	v_readlane_b32 s95, v252, 5

.LBB0_809:
	ds_write_b128 v20, v[4:7]
	s_waitcnt lgkmcnt(0)
	s_barrier
	s_waitcnt vmcnt(0)
	ds_read2st64_b32 v[0:1], v15 offset1:1
	ds_read2st64_b32 v[2:3], v15 offset0:2 offset1:3
	ds_read2st64_b32 v[4:5], v15 offset0:4 offset1:5
	ds_read2st64_b32 v[6:7], v15 offset0:6 offset1:7
	v_lshl_add_u64 v[24:25], s[8:9], 1, v[12:13]
	s_waitcnt lgkmcnt(3)
	v_cvt_pk_bf16_f32 v0, v0, v1
	s_waitcnt lgkmcnt(2)
	v_cvt_pk_bf16_f32 v1, v2, v3
	s_waitcnt lgkmcnt(1)
	v_cvt_pk_bf16_f32 v2, v4, v5
	v_or_b32_e32 v4, s18, v8
	v_ashrrev_i32_e32 v5, 31, v4
	s_waitcnt lgkmcnt(0)
	v_cvt_pk_bf16_f32 v3, v6, v7
	v_lshlrev_b64 v[4:5], 11, v[4:5]
	ds_read2st64_b32 v[6:7], v21 offset1:1
	ds_read2st64_b32 v[26:27], v21 offset0:2 offset1:3
	ds_read2st64_b32 v[28:29], v21 offset0:4 offset1:5
	ds_read2st64_b32 v[30:31], v21 offset0:6 offset1:7
	v_lshl_add_u64 v[4:5], v[24:25], 0, v[4:5]
	global_store_dwordx4 v[4:5], v[0:3], off sc1
	v_add_u32_e32 v4, s18, v17
	v_ashrrev_i32_e32 v5, 31, v4
	v_lshlrev_b64 v[4:5], 11, v[4:5]
	s_add_i32 s17, s17, s82
	s_add_i32 s3, s3, s14
	s_waitcnt lgkmcnt(3)
	v_cvt_pk_bf16_f32 v0, v6, v7
	s_waitcnt lgkmcnt(2)
	v_cvt_pk_bf16_f32 v1, v26, v27
	s_waitcnt lgkmcnt(1)
	v_cvt_pk_bf16_f32 v2, v28, v29
	s_waitcnt lgkmcnt(0)
	v_cvt_pk_bf16_f32 v3, v30, v31
	v_lshl_add_u64 v[4:5], v[24:25], 0, v[4:5]
	s_cmpk_lt_i32 s17, 0x160
	v_add_u32_e32 v22, s15, v22
	global_store_dwordx4 v[4:5], v[0:3], off sc1
	s_cbranch_scc0 .LBB0_828

.LBB0_830:
	s_waitcnt vmcnt(0)
	ds_write_b128 v25, v[0:3]
	s_waitcnt lgkmcnt(0)
	s_barrier
	ds_read2st64_b32 v[0:1], v21 offset1:1
	ds_read2st64_b32 v[2:3], v21 offset0:2 offset1:3
	ds_read2st64_b32 v[18:19], v21 offset0:4 offset1:5
	ds_read2st64_b32 v[28:29], v21 offset0:6 offset1:7
	ds_read2st64_b32 v[30:31], v26 offset1:1
	ds_read2st64_b32 v[32:33], v26 offset0:2 offset1:3
	ds_read2st64_b32 v[34:35], v26 offset0:4 offset1:5
	ds_read2st64_b32 v[36:37], v26 offset0:6 offset1:7
	s_waitcnt lgkmcnt(7)
	v_cvt_pk_bf16_f32 v0, v0, v1
	s_waitcnt lgkmcnt(6)
	v_cvt_pk_bf16_f32 v1, v2, v3
	s_waitcnt lgkmcnt(5)
	v_cvt_pk_bf16_f32 v2, v18, v19
	v_add_u32_e32 v18, s9, v20
	v_ashrrev_i32_e32 v19, 31, v18
	s_waitcnt lgkmcnt(4)
	v_cvt_pk_bf16_f32 v3, v28, v29
	v_lshlrev_b64 v[28:29], 8, v[18:19]
	v_add_u32_e32 v18, 32, v18
	v_ashrrev_i32_e32 v19, 31, v18
	v_lshl_add_u64 v[28:29], v[6:7], 0, v[28:29]
	v_lshlrev_b64 v[18:19], 8, v[18:19]
	s_add_i32 s13, s13, s82
	s_add_i32 s3, s3, s8
	s_add_i32 s9, s9, s12
	global_store_dwordx4 v[28:29], v[0:3], off sc1
	v_lshl_add_u64 v[18:19], v[6:7], 0, v[18:19]
	s_cmp_lt_i32 s13, 32
	s_waitcnt lgkmcnt(3)
	v_cvt_pk_bf16_f32 v0, v30, v31
	s_waitcnt lgkmcnt(2)
	v_cvt_pk_bf16_f32 v1, v32, v33
	s_waitcnt lgkmcnt(1)
	v_cvt_pk_bf16_f32 v2, v34, v35
	s_waitcnt lgkmcnt(0)
	v_cvt_pk_bf16_f32 v3, v36, v37
	global_store_dwordx4 v[18:19], v[0:3], off sc1
	s_cbranch_scc0 .LBB0_847

.LBB0_849:
	s_waitcnt vmcnt(1)
	ds_write_b128 v18, v[4:7]
	s_waitcnt vmcnt(0)
	ds_write_b128 v19, v[0:3]
	s_waitcnt lgkmcnt(0)
	s_barrier
	ds_read2st64_b32 v[0:1], v14 offset1:1
	ds_read2st64_b32 v[2:3], v14 offset0:2 offset1:3
	ds_read2st64_b32 v[4:5], v14 offset0:4 offset1:5
	ds_read2st64_b32 v[6:7], v14 offset0:6 offset1:7
	s_add_i32 s0, s3, s6
	s_waitcnt lgkmcnt(3)
	v_cvt_pk_bf16_f32 v0, v0, v1
	s_waitcnt lgkmcnt(2)
	v_cvt_pk_bf16_f32 v1, v2, v3
	s_waitcnt lgkmcnt(1)
	v_cvt_pk_bf16_f32 v2, v4, v5
	v_or_b32_e32 v4, s5, v12
	s_ashr_i32 s1, s0, 31
	v_ashrrev_i32_e32 v5, 31, v4
	v_lshl_add_u64 v[22:23], s[0:1], 1, v[10:11]
	s_waitcnt lgkmcnt(0)
	v_cvt_pk_bf16_f32 v3, v6, v7
	v_lshlrev_b64 v[4:5], 12, v[4:5]
	ds_read2st64_b32 v[6:7], v20 offset1:1
	ds_read2st64_b32 v[24:25], v20 offset0:2 offset1:3
	ds_read2st64_b32 v[26:27], v20 offset0:4 offset1:5
	ds_read2st64_b32 v[28:29], v20 offset0:6 offset1:7
	v_lshl_add_u64 v[4:5], v[22:23], 0, v[4:5]
	global_store_dwordx4 v[4:5], v[0:3], off sc1
	v_add_u32_e32 v4, s5, v16
	v_ashrrev_i32_e32 v5, 31, v4
	v_lshlrev_b64 v[4:5], 12, v[4:5]
	s_add_i32 s9, s9, s82
	s_add_i32 s3, s3, s8
	s_waitcnt lgkmcnt(3)
	v_cvt_pk_bf16_f32 v0, v6, v7
	s_waitcnt lgkmcnt(2)
	v_cvt_pk_bf16_f32 v1, v24, v25
	s_waitcnt lgkmcnt(1)
	v_cvt_pk_bf16_f32 v2, v26, v27
	s_waitcnt lgkmcnt(0)
	v_cvt_pk_bf16_f32 v3, v28, v29
	v_lshl_add_u64 v[4:5], v[22:23], 0, v[4:5]
	s_cmpk_lt_i32 s9, 0x100
	global_store_dwordx4 v[4:5], v[0:3], off sc1
	s_cbranch_scc0 .LBB0_854

.LBB0_944:
	v_lshl_add_u64 v[142:143], v[140:141], 0, s[64:65]
	v_add_co_u32_e32 v166, vcc, 0xbfff000, v142
	ds_read_b128 v[150:153], v130
	ds_read_b128 v[154:157], v130 offset:1152
	ds_read_b128 v[158:161], v130 offset:2304
	ds_read_b128 v[162:165], v130 offset:3456
	v_addc_co_u32_e32 v167, vcc, 0, v143, vcc
	v_add_co_u32_e32 v168, vcc, 0xc007000, v142
	s_add_u32 s64, s64, 0x20000
	s_nop 0
	v_addc_co_u32_e32 v169, vcc, 0, v143, vcc
	v_add_co_u32_e32 v170, vcc, 0xc00f000, v142
	s_addc_u32 s65, s65, 0
	s_nop 0
	v_addc_co_u32_e32 v171, vcc, 0, v143, vcc
	v_add_co_u32_e32 v142, vcc, 0xc017000, v142
	v_add_u32_e32 v130, 0x1200, v130
	s_cmp_lg_u32 s64, 0x80000
	v_addc_co_u32_e32 v143, vcc, 0, v143, vcc
	s_waitcnt lgkmcnt(3)
	global_store_dwordx4 v[166:167], v[150:153], off offset:2816 sc1
	s_waitcnt lgkmcnt(2)
	global_store_dwordx4 v[168:169], v[154:157], off offset:2816 sc1
	s_waitcnt lgkmcnt(1)
	global_store_dwordx4 v[170:171], v[158:161], off offset:2816 sc1
	s_waitcnt lgkmcnt(0)
	global_store_dwordx4 v[142:143], v[162:165], off offset:2816 sc1
	s_cbranch_scc1 .LBB0_944
	s_waitcnt lgkmcnt(0)

.LBB0_961:
	v_lshl_add_u64 v[20:21], v[0:1], 0, s[58:59]
	v_add_co_u32_e32 v22, vcc, 0xe00000, v20
	s_waitcnt lgkmcnt(0)
	ds_read_b128 v[4:7], v2
	ds_read_b128 v[8:11], v2 offset:1152
	ds_read_b128 v[12:15], v2 offset:2304
	ds_read_b128 v[16:19], v2 offset:3456
	v_addc_co_u32_e32 v23, vcc, 0, v21, vcc
	v_add_co_u32_e32 v24, vcc, 0xe01000, v20
	s_add_u32 s58, s58, 0x6000
	s_nop 0
	v_addc_co_u32_e32 v25, vcc, 0, v21, vcc
	v_add_co_u32_e32 v26, vcc, 0xe03000, v20
	s_addc_u32 s59, s59, 0
	s_nop 0
	v_addc_co_u32_e32 v27, vcc, 0, v21, vcc
	v_add_co_u32_e32 v20, vcc, 0xe04000, v20
	v_add_u32_e32 v2, 0x1200, v2
	s_cmp_lg_u32 s58, 0x18000
	v_addc_co_u32_e32 v21, vcc, 0, v21, vcc
	s_waitcnt lgkmcnt(3)
	global_store_dwordx4 v[22:23], v[4:7], off sc1
	s_waitcnt lgkmcnt(2)
	global_store_dwordx4 v[24:25], v[8:11], off offset:2048 sc1
	s_waitcnt lgkmcnt(1)
	global_store_dwordx4 v[26:27], v[12:15], off sc1
	s_waitcnt lgkmcnt(0)
	global_store_dwordx4 v[20:21], v[16:19], off offset:2048 sc1
	s_cbranch_scc1 .LBB0_961
	s_waitcnt lgkmcnt(0)
	s_branch .LBB0_932

.LBB0_1157:
	v_lshl_add_u64 v[20:21], v[0:1], 0, s[48:49]
	v_add_co_u32_e32 v22, vcc, 0x6000000, v20
	ds_read_b128 v[4:7], v2
	ds_read_b128 v[8:11], v2 offset:1152
	ds_read_b128 v[12:15], v2 offset:2304
	ds_read_b128 v[16:19], v2 offset:3456
	v_addc_co_u32_e32 v23, vcc, 0, v21, vcc
	v_add_co_u32_e32 v24, vcc, 0x600c000, v20
	s_add_u32 s48, s48, 0x30000
	s_nop 0
	v_addc_co_u32_e32 v25, vcc, 0, v21, vcc
	v_add_co_u32_e32 v26, vcc, 0x6018000, v20
	s_addc_u32 s49, s49, 0
	s_nop 0
	v_addc_co_u32_e32 v27, vcc, 0, v21, vcc
	v_add_co_u32_e32 v20, vcc, 0x6024000, v20
	v_add_u32_e32 v2, 0x1200, v2
	s_cmp_lg_u32 s48, 0xc0000
	v_addc_co_u32_e32 v21, vcc, 0, v21, vcc
	s_waitcnt lgkmcnt(3)
	global_store_dwordx4 v[22:23], v[4:7], off sc1
	s_waitcnt lgkmcnt(2)
	global_store_dwordx4 v[24:25], v[8:11], off sc1
	s_waitcnt lgkmcnt(1)
	global_store_dwordx4 v[26:27], v[12:15], off sc1
	s_waitcnt lgkmcnt(0)
	global_store_dwordx4 v[20:21], v[16:19], off sc1
	s_cbranch_scc1 .LBB0_1157
	s_waitcnt lgkmcnt(0)
	s_add_i32 s66, s66, s82
	s_add_i32 s65, s65, s82
	s_cmpk_gt_i32 s66, 0x2ff
	s_cbranch_scc0 .LBB0_1020

.LBB0_1255:
	s_cmp_lt_i32 s84, 16
	s_cselect_b64 s[4:5], -1, 0
	s_and_b64 s[0:1], s[4:5], s[0:1]
	s_andn2_b64 vcc, exec, s[0:1]
	s_cbranch_vccnz .LBB0_1273
	v_mov_b32_e32 v2, v181
	s_cmpk_gt_i32 s2, 0x3ff
	s_cbranch_scc1 .LBB0_1273
	s_add_u32 s6, s34, 0x6000000
	s_addc_u32 s7, s35, 0
	s_add_u32 s3, s34, 0x2200000
	v_ashrrev_i32_e32 v0, 4, v2
	s_addc_u32 s14, s35, 0
	v_lshlrev_b32_e32 v182, 7, v0
	v_xor_b32_e32 v0, v0, v2
	s_add_u32 s15, s34, 0x2800000
	v_lshlrev_b32_e32 v0, 4, v0
	s_addc_u32 s16, s35, 0
	s_not_b32 s0, s2
	v_mov_b32_e32 v1, 0
	v_and_b32_e32 v0, 0xf0, v0
	s_add_i32 s17, s82, s0
	v_lshl_add_u64 v[4:5], s[34:35], 0, v[0:1]
	s_mov_b64 s[0:1], 0x900000
	v_lshl_add_u64 v[184:185], v[4:5], 0, s[0:1]
	s_mov_b32 s0, 0x2aaaaaab
	v_mul_hi_i32 v5, v2, s0
	v_add_u32_e32 v0, 0x200, v2
	s_waitcnt lgkmcnt(0)
	v_lshrrev_b32_e32 v6, 31, v5
	v_ashrrev_i32_e32 v5, 2, v5
	v_add_u32_e32 v16, v5, v6
	v_mul_hi_i32 v5, v0, s0
	v_add_u32_e32 v4, 0x400, v2
	v_lshrrev_b32_e32 v6, 31, v5
	v_ashrrev_i32_e32 v5, 2, v5
	v_add_u32_e32 v17, v5, v6
	v_mul_hi_i32 v5, v4, s0
	v_bfe_u32 v3, v2, 5, 1
	v_lshrrev_b32_e32 v6, 31, v5
	v_ashrrev_i32_e32 v5, 2, v5
	s_movk_i32 s10, 0xc0
	s_movk_i32 s9, 0xffe8
	v_add_u32_e32 v18, v5, v6
	v_mul_lo_u32 v5, v16, s10
	v_mad_u64_u32 v[6:7], s[0:1], v16, s9, v[2:3]
	v_lshl_add_u32 v186, v6, 3, v5
	v_mul_lo_u32 v5, v17, s10
	v_mad_u64_u32 v[8:9], s[0:1], v17, s9, v[0:1]
	v_ashrrev_i32_e32 v12, 3, v0
	v_lshlrev_b32_e32 v0, 3, v2
	v_lshl_add_u32 v188, v8, 3, v5
	v_mad_u64_u32 v[4:5], s[0:1], v18, s9, v[4:5]
	v_and_b32_e32 v14, 56, v0
	v_mbcnt_lo_u32_b32 v0, -1, 0
	s_movk_i32 s0, 0x190
	v_mbcnt_hi_u32_b32 v0, -1, v0
	v_mul_lo_u32 v9, v17, s0
	v_and_b32_e32 v17, 64, v0
	v_lshl_add_u32 v5, v6, 4, 0
	v_lshl_add_u32 v6, v8, 4, 0
	v_mul_lo_u32 v8, v16, s0
	v_xor_b32_e32 v16, 32, v0
	v_add_u32_e32 v17, 64, v17
	v_cmp_lt_i32_e32 vcc, v16, v17
	v_and_b32_e32 v214, 31, v2
	v_lshlrev_b32_e32 v216, 4, v2
	v_cndmask_b32_e32 v0, v0, v16, vcc
	s_add_i32 s18, 0, 0x12000
	v_mov_b32_e32 v20, 0xf0
	v_lshlrev_b32_e32 v180, 3, v3
	v_lshlrev_b32_e32 v218, 2, v0
	v_lshl_add_u32 v0, v214, 8, s18
	v_bitop3_b32 v21, v216, 16, v20 bitop3:0x6c
	v_add3_u32 v220, v0, v21, v180
	v_bitop3_b32 v21, v216, 32, v20 bitop3:0x6c
	v_bitop3_b32 v22, v216, 48, v20 bitop3:0x6c
	s_movk_i32 s1, 0x50
	v_add3_u32 v221, v0, v21, v180
	v_add3_u32 v222, v0, v22, v180
	v_bitop3_b32 v21, v216, 64, v20 bitop3:0x6c
	v_bitop3_b32 v22, v216, s1, v20 bitop3:0x6c
	s_movk_i32 s1, 0x60
	v_add3_u32 v223, v0, v21, v180
	v_bitop3_b32 v21, v216, s1, v20 bitop3:0x6c
	s_movk_i32 s1, 0x70
	v_add3_u32 v224, v0, v22, v180
	v_bitop3_b32 v22, v216, s1, v20 bitop3:0x6c
	s_movk_i32 s1, 0x80
	v_add3_u32 v225, v0, v21, v180
	v_bitop3_b32 v21, v216, s1, v20 bitop3:0x6c
	s_movk_i32 s1, 0x90
	v_add3_u32 v226, v0, v22, v180
	v_bitop3_b32 v22, v216, s1, v20 bitop3:0x6c
	s_movk_i32 s1, 0xa0
	v_ashrrev_i32_e32 v10, 3, v2
	v_add3_u32 v227, v0, v21, v180
	v_bitop3_b32 v21, v216, s1, v20 bitop3:0x6c
	s_movk_i32 s1, 0xb0
	v_ashrrev_i32_e32 v11, 31, v10
	v_add3_u32 v228, v0, v22, v180
	v_bitop3_b32 v22, v216, s1, v20 bitop3:0x6c
	s_movk_i32 s1, 0xd0
	s_movk_i32 s8, 0xf0
	v_lshlrev_b64 v[192:193], 13, v[10:11]
	v_ashrrev_i32_e32 v13, 31, v12
	v_mul_lo_u32 v11, v18, s0
	s_movk_i32 s0, 0x88
	v_add3_u32 v229, v0, v21, v180
	v_add3_u32 v230, v0, v22, v180
	v_bitop3_b32 v21, v216, s10, v20 bitop3:0x6c
	v_bitop3_b32 v22, v216, s1, v20 bitop3:0x6c
	s_movk_i32 s1, 0xe0
	v_ashrrev_i32_e32 v15, 6, v2
	v_lshlrev_b64 v[194:195], 13, v[12:13]
	v_mul_lo_u32 v10, v10, s0
	v_mul_lo_u32 v12, v12, s0
	s_movk_i32 s0, 0x2200
	v_bfe_u32 v2, v2, 4, 2
	v_and_b32_e32 v19, 0xf0, v216
	v_add3_u32 v231, v0, v21, v180
	v_bitop3_b32 v20, v216, s1, v20 bitop3:0x6c
	v_bitop3_b32 v21, v216, s8, v216 bitop3:0xc
	v_lshlrev_b32_e32 v215, 5, v15
	v_mul_lo_u32 v7, v18, s10
	v_lshl_add_u32 v13, v3, 4, 0
	v_mul_lo_u32 v15, v15, s0
	s_movk_i32 s0, 0x110
	v_mul_u32_u24_e32 v16, 0x110, v214
	v_add3_u32 v219, v0, v19, v180
	v_add3_u32 v232, v0, v22, v180
	v_add3_u32 v233, v0, v20, v180
	v_add3_u32 v234, v0, v21, v180
	v_lshl_or_b32 v0, v2, 12, v19
	v_lshl_add_u32 v190, v4, 3, v7
	v_lshl_add_u32 v4, v4, 4, 0
	v_lshl_add_u32 v7, v14, 1, 0
	v_lshlrev_b32_e32 v217, 2, v3
	v_sub_u32_e32 v3, v13, v180
	v_add3_u32 v16, 0, v15, v16
	v_add_u32_e32 v196, 0x1000, v182
	v_add_u32_e32 v198, 0x2000, v182
	v_add_u32_e32 v200, 0x3000, v182
	v_mul_u32_u24_e32 v17, 0x190, v214
	v_mul_u32_u24_e32 v18, 0x88, v214
	v_lshl_add_u64 v[202:203], s[34:35], 0, v[0:1]
	v_mad_u32_u24 v0, v2, s0, v15
	s_movk_i32 s0, 0x6400
	v_ashrrev_i32_e32 v187, 31, v186
	v_ashrrev_i32_e32 v189, 31, v188
	v_ashrrev_i32_e32 v191, 31, v190
	s_mov_b32 s9, 0
	v_ashrrev_i32_e32 v183, 31, v182
	v_ashrrev_i32_e32 v197, 31, v196
	v_ashrrev_i32_e32 v199, 31, v198
	v_ashrrev_i32_e32 v201, 31, v200
	v_add3_u32 v235, v0, v19, 0
	s_movk_i32 s19, 0x1800
	v_lshlrev_b32_e32 v204, 1, v14
	v_add_u32_e32 v236, v5, v8
	v_add_u32_e32 v237, v6, v9
	v_add_u32_e32 v238, v4, v11
	v_add3_u32 v239, v7, v10, s0
	v_add3_u32 v240, v7, v12, s0
	v_add_u32_e32 v241, v13, v17
	s_mov_b32 s22, 0xf149f2ca
	s_mov_b32 s23, 0x41000000
	v_add_u32_e32 v242, v3, v18
	v_add_u32_e32 v243, v16, v180
	s_mov_b32 s36, 0xc004000
	s_mov_b32 s37, 0xc008000
	s_mov_b32 s38, 0xc00c000
	v_mov_b32_e32 v244, 0xf149f2ca
	s_mov_b32 s0, s2
	s_mov_b32 s39, 0
	v_lshrrev_b32_e32 v245, 3, v181
	v_mul_u32_u24_e32 v245, 0x90, v245
	v_and_b32_e32 v246, 7, v181
	v_lshrrev_b32_e32 v247, 1, v246
	v_lshl_add_u32 v245, v247, 5, v245
	v_and_b32_e32 v246, 1, v246
	v_lshl_add_u32 v245, v246, 3, v245
	v_add_u32_e32 v245, 0x6400, v245
	v_add_u32_e32 v246, 0x2400, v245
	v_and_b32_e32 v247, 31, v181
	v_mul_u32_u24_e32 v247, 0x90, v247
	v_bfe_u32 v248, v181, 5, 1
	v_lshl_add_u32 v247, v248, 4, v247
	v_add_u32_e32 v247, 0x6400, v247
.LBB0_1258:
	s_bfe_u32 s41, s0, 0x20004
	s_and_b32 s40, s0, 15
	s_lshl_b32 s0, s0, 2
	s_and_b32 s0, s0, 0xffffff00
	v_subrev_u32_e32 v2, s0, v215
	v_add_u32_e32 v206, 0xf00, v2
	v_or_b32_e32 v208, v206, v214
	s_lshl_b32 s8, s41, 12
	v_ashrrev_i32_e32 v209, 31, v208
	v_lshl_add_u64 v[4:5], s[8:9], 0, v[208:209]
	v_mov_b64_e32 v[6:7], s[6:7]
	v_mad_u64_u32 v[6:7], s[10:11], v4, s19, v[6:7]
	v_mad_i32_i24 v7, v5, s19, v7
	s_mul_i32 s8, s40, 0x180
	v_lshl_add_u64 v[4:5], v[6:7], 0, s[8:9]
	v_lshlrev_b32_e32 v0, 1, v180
	v_lshl_add_u64 v[4:5], v[4:5], 0, v[0:1]
	global_load_dwordx4 v[112:115], v[4:5], off
	global_load_dwordx4 v[116:119], v[4:5], off offset:32
	global_load_dwordx4 v[120:123], v[4:5], off offset:64
	global_load_dwordx4 v[124:127], v[4:5], off offset:96
	global_load_dwordx4 v[128:131], v[4:5], off offset:128
	global_load_dwordx4 v[132:135], v[4:5], off offset:160
	global_load_dwordx4 v[136:139], v[4:5], off offset:192
	global_load_dwordx4 v[140:143], v[4:5], off offset:224
	global_load_dwordx4 v[144:147], v[4:5], off offset:256
	global_load_dwordx4 v[148:151], v[4:5], off offset:288
	global_load_dwordx4 v[152:155], v[4:5], off offset:320
	global_load_dwordx4 v[156:159], v[4:5], off offset:352
	s_lshl_b32 s8, s40, 15
	v_add_u32_e32 v0, s18, v216
	v_lshl_add_u64 v[4:5], v[184:185], 0, s[8:9]
	v_readfirstlane_b32 s1, v0
	v_add_u32_e32 v3, 0x2000, v0
	v_lshl_add_u64 v[6:7], v[182:183], 1, v[4:5]
	s_mov_b32 m0, s1
	v_readfirstlane_b32 s1, v3
	v_add_u32_e32 v3, 0x4000, v0
	global_load_lds_dwordx4 v[6:7], off
	v_lshl_add_u64 v[6:7], v[196:197], 1, v[4:5]
	s_mov_b32 m0, s1
	v_readfirstlane_b32 s1, v3
	v_add_u32_e32 v0, 0x6000, v0
	global_load_lds_dwordx4 v[6:7], off
	v_lshl_add_u64 v[6:7], v[198:199], 1, v[4:5]
	s_mov_b32 m0, s1
	v_readfirstlane_b32 s1, v0
	global_load_lds_dwordx4 v[6:7], off
	v_lshl_add_u64 v[4:5], v[200:201], 1, v[4:5]
	s_mov_b32 m0, s1
	s_cmpk_eq_i32 s0, 0x1000
	global_load_lds_dwordx4 v[4:5], off
	s_cbranch_scc1 .LBB0_1269
	s_sub_i32 s0, 0x1000, s0
	s_lshr_b32 s42, s0, 6
	s_mul_i32 s0, s41, 0x180000
	s_add_u32 s0, s3, s0
	s_addc_u32 s1, s14, 0
	s_lshl_b32 s8, s41, 20
	s_add_u32 s10, s15, s8
	s_addc_u32 s11, s16, 0
	v_lshl_add_u64 v[4:5], s[10:11], 0, v[192:193]
	v_lshl_add_u64 v[6:7], s[10:11], 0, v[194:195]
	v_mov_b32_e32 v205, v1
	v_lshl_add_u64 v[210:211], v[4:5], 0, v[204:205]
	v_lshl_add_u64 v[212:213], v[6:7], 0, v[204:205]
	v_lshl_add_u64 v[4:5], v[190:191], 1, s[0:1]
	global_load_dwordx4 v[164:167], v[212:213], off
	global_load_dwordx4 v[160:163], v[210:211], off
	v_lshl_add_u64 v[6:7], v[188:189], 1, s[0:1]
	global_load_dwordx4 v[176:179], v[4:5], off
	global_load_dwordx4 v[168:171], v[6:7], off
	v_lshl_add_u64 v[4:5], v[186:187], 1, s[0:1]
	global_load_dwordx4 v[172:175], v[4:5], off
	v_mov_b32_e32 v14, v1
	v_mov_b32_e32 v15, v1
	v_add_u32_e32 v207, 0xf1f, v2
	v_mov_b32_e32 v0, v1
	v_mov_b32_e32 v2, v1
	v_mov_b32_e32 v3, v1
	v_mov_b32_e32 v4, v1
	v_mov_b32_e32 v5, v1
	v_mov_b32_e32 v6, v1
	v_mov_b32_e32 v7, v1
	v_mov_b32_e32 v8, v1
	v_mov_b32_e32 v9, v1
	v_mov_b32_e32 v10, v1
	v_mov_b32_e32 v11, v1
	v_mov_b32_e32 v12, v1
	v_mov_b32_e32 v13, v1
	v_mov_b64_e32 v[78:79], v[14:15]
	v_mov_b64_e32 v[62:63], v[14:15]
	v_mov_b64_e32 v[46:47], v[14:15]
	v_mov_b64_e32 v[30:31], v[14:15]
	s_mov_b32 s43, 0
	v_mov_b32_e32 v209, 0xf149f2ca
	v_mov_b32_e32 v205, 0
	v_mov_b64_e32 v[76:77], v[12:13]
	v_mov_b64_e32 v[74:75], v[10:11]
	v_mov_b64_e32 v[72:73], v[8:9]
	v_mov_b64_e32 v[70:71], v[6:7]
	v_mov_b64_e32 v[68:69], v[4:5]
	v_mov_b64_e32 v[66:67], v[2:3]
	v_mov_b64_e32 v[64:65], v[0:1]
	v_mov_b64_e32 v[60:61], v[12:13]
	v_mov_b64_e32 v[58:59], v[10:11]
	v_mov_b64_e32 v[56:57], v[8:9]
	v_mov_b64_e32 v[54:55], v[6:7]
	v_mov_b64_e32 v[52:53], v[4:5]
	v_mov_b64_e32 v[50:51], v[2:3]
	v_mov_b64_e32 v[48:49], v[0:1]
	v_mov_b64_e32 v[44:45], v[12:13]
	v_mov_b64_e32 v[42:43], v[10:11]
	v_mov_b64_e32 v[40:41], v[8:9]
	v_mov_b64_e32 v[38:39], v[6:7]
	v_mov_b64_e32 v[36:37], v[4:5]
	v_mov_b64_e32 v[34:35], v[2:3]
	v_mov_b64_e32 v[32:33], v[0:1]
	v_mov_b64_e32 v[28:29], v[12:13]
	v_mov_b64_e32 v[26:27], v[10:11]
	v_mov_b64_e32 v[24:25], v[8:9]
	v_mov_b64_e32 v[22:23], v[6:7]
	v_mov_b64_e32 v[20:21], v[4:5]
	v_mov_b64_e32 v[18:19], v[2:3]
	v_mov_b64_e32 v[16:17], v[0:1]
	s_mov_b32 s44, 0
	s_waitcnt vmcnt(0) lgkmcnt(0)
	s_barrier
	ds_write_b128 v236, v[172:175]
	ds_write_b128 v237, v[168:171]
	ds_write_b128 v238, v[176:179]
	ds_write2_b64 v245, v[160:161], v[162:163] offset1:2
	ds_write2_b64 v246, v[164:165], v[166:167] offset1:2
	v_add_u32_e32 v236, 0x1a000, v236
	v_add_u32_e32 v237, 0x1a000, v237
	v_add_u32_e32 v238, 0x1a000, v238
	v_add_u32_e32 v245, 0x4800, v245
	v_add_u32_e32 v246, 0x4800, v246
	s_cmp_lt_u32 s42, 2
	s_cbranch_scc1 .Lattn_p1
	s_mov_b32 s8, 64
	s_mul_i32 s10, s8, 0x180
	s_mul_hi_u32 s11, s8, 0x180
	s_add_u32 s10, s0, s10
	s_addc_u32 s11, s1, s11
	v_lshl_add_u64 v[2:3], v[186:187], 1, s[10:11]
	v_lshl_add_u64 v[4:5], v[188:189], 1, s[10:11]
	global_load_dwordx4 v[172:175], v[2:3], off
	global_load_dwordx4 v[168:171], v[4:5], off
	v_lshl_add_u64 v[2:3], v[190:191], 1, s[10:11]
	s_lshl_b64 s[10:11], s[8:9], 1
	v_lshl_add_u64 v[4:5], v[210:211], 0, s[10:11]
	global_load_dwordx4 v[176:179], v[2:3], off
	global_load_dwordx4 v[160:163], v[4:5], off
	v_lshl_add_u64 v[2:3], v[212:213], 0, s[10:11]
	global_load_dwordx4 v[164:167], v[2:3], off
.Lattn_p1:
	s_waitcnt lgkmcnt(0)
	s_barrier
	s_branch .LBB0_1262
.LBB0_1260:
	v_sub_f32_e32 v0, v96, v209
	v_exp_f32_e32 v0, v0
	v_sub_f32_e32 v2, v97, v209
	v_exp_f32_e32 v6, v2
	v_sub_f32_e32 v2, v98, v209
	v_exp_f32_e32 v7, v2
	v_add_f32_e32 v2, 0, v0
	v_add_f32_e32 v2, v6, v2
	v_sub_f32_e32 v8, v103, v209
	v_add_f32_e32 v14, v7, v2
	v_sub_f32_e32 v2, v99, v209
	v_exp_f32_e32 v15, v2
	v_sub_f32_e32 v2, v100, v209
	v_exp_f32_e32 v96, v2
	v_sub_f32_e32 v2, v101, v209
	v_exp_f32_e32 v97, v2
	v_sub_f32_e32 v2, v102, v209
	v_add_u32_e32 v99, 0x6000, v242
	v_exp_f32_e32 v98, v2
	ds_read_b128 v[2:5], v247
	v_exp_f32_e32 v100, v8
	v_cvt_pk_bf16_f32 v6, v0, v6
	v_add_u32_e32 v0, 0x7000, v242
	ds_read_b128 v[10:13], v247 offset:4608
	v_cvt_pk_bf16_f32 v7, v7, v15
	v_cvt_pk_bf16_f32 v8, v96, v97
	v_cvt_pk_bf16_f32 v9, v98, v100
	v_add_u32_e32 v101, 0x8000, v242
	s_waitcnt lgkmcnt(1)
	v_mfma_f32_32x32x16_bf16 v[64:79], v[2:5], v[6:9], v[64:79]
	v_add_f32_e32 v2, v15, v14
	v_add_f32_e32 v14, v96, v2
	v_sub_f32_e32 v2, v104, v209
	v_exp_f32_e32 v15, v2
	ds_read_b128 v[2:5], v247 offset:9216
	v_add_u32_e32 v104, 0x9000, v242
	v_sub_f32_e32 v96, v105, v209
	s_waitcnt lgkmcnt(1)
	v_mfma_f32_32x32x16_bf16 v[48:63], v[10:13], v[6:9], v[48:63]
	v_sub_f32_e32 v10, v106, v209
	v_exp_f32_e32 v102, v10
	v_sub_f32_e32 v10, v107, v209
	v_exp_f32_e32 v103, v10
	ds_read_b128 v[10:13], v247 offset:13824
	v_exp_f32_e32 v96, v96
	s_waitcnt lgkmcnt(1)
	v_mfma_f32_32x32x16_bf16 v[32:47], v[2:5], v[6:9], v[32:47]
	v_sub_f32_e32 v2, v108, v209
	v_exp_f32_e32 v105, v2
	v_sub_f32_e32 v2, v109, v209
	v_exp_f32_e32 v106, v2
	v_sub_f32_e32 v2, v110, v209
	v_exp_f32_e32 v107, v2
	ds_read_b128 v[2:5], v247 offset:32
	s_waitcnt lgkmcnt(1)
	v_mfma_f32_32x32x16_bf16 v[16:31], v[10:13], v[6:9], v[16:31]
	v_sub_f32_e32 v6, v111, v209
	v_exp_f32_e32 v108, v6
	ds_read_b128 v[10:13], v247 offset:4640
	v_cvt_pk_bf16_f32 v6, v15, v96
	v_cvt_pk_bf16_f32 v7, v102, v103
	v_cvt_pk_bf16_f32 v8, v105, v106
	v_cvt_pk_bf16_f32 v9, v107, v108
	s_waitcnt lgkmcnt(1)
	s_nop 0
	v_mfma_f32_32x32x16_bf16 v[64:79], v[2:5], v[6:9], v[64:79]
	v_add_f32_e32 v2, v97, v14
	v_add_f32_e32 v2, v98, v2
	v_add_f32_e32 v2, v100, v2
	v_add_f32_e32 v14, v15, v2
	v_sub_f32_e32 v2, v80, v209
	v_exp_f32_e32 v15, v2
	ds_read_b128 v[2:5], v247 offset:9248
	s_waitcnt lgkmcnt(1)
	v_mfma_f32_32x32x16_bf16 v[48:63], v[10:13], v[6:9], v[48:63]
	v_sub_f32_e32 v10, v81, v209
	v_exp_f32_e32 v80, v10
	v_sub_f32_e32 v10, v82, v209
	v_exp_f32_e32 v81, v10
	v_sub_f32_e32 v10, v83, v209
	v_exp_f32_e32 v82, v10
	ds_read_b128 v[10:13], v247 offset:13856
	s_waitcnt lgkmcnt(1)
	v_mfma_f32_32x32x16_bf16 v[32:47], v[2:5], v[6:9], v[32:47]
	v_sub_f32_e32 v2, v84, v209
	v_exp_f32_e32 v83, v2
	v_sub_f32_e32 v2, v85, v209
	v_exp_f32_e32 v84, v2
	v_sub_f32_e32 v2, v86, v209
	v_exp_f32_e32 v85, v2
	ds_read_b128 v[2:5], v247 offset:64
	s_waitcnt lgkmcnt(1)
	v_mfma_f32_32x32x16_bf16 v[16:31], v[10:13], v[6:9], v[16:31]
	v_sub_f32_e32 v6, v87, v209
	v_exp_f32_e32 v86, v6
	ds_read_b128 v[10:13], v247 offset:4672
	v_cvt_pk_bf16_f32 v6, v15, v80
	v_cvt_pk_bf16_f32 v7, v81, v82
	v_cvt_pk_bf16_f32 v8, v83, v84
	v_cvt_pk_bf16_f32 v9, v85, v86
	s_waitcnt lgkmcnt(1)
	s_nop 0
	v_mfma_f32_32x32x16_bf16 v[64:79], v[2:5], v[6:9], v[64:79]
	v_add_f32_e32 v2, v96, v14
	v_add_f32_e32 v2, v102, v2
	v_add_f32_e32 v2, v103, v2
	v_add_f32_e32 v14, v105, v2
	v_sub_f32_e32 v2, v88, v209
	v_exp_f32_e32 v87, v2
	ds_read_b128 v[2:5], v247 offset:9280
	s_waitcnt lgkmcnt(1)
	v_mfma_f32_32x32x16_bf16 v[48:63], v[10:13], v[6:9], v[48:63]
	v_sub_f32_e32 v10, v89, v209
	v_exp_f32_e32 v88, v10
	v_sub_f32_e32 v10, v90, v209
	v_exp_f32_e32 v89, v10
	v_sub_f32_e32 v10, v91, v209
	v_exp_f32_e32 v90, v10
	ds_read_b128 v[10:13], v247 offset:13888
	s_waitcnt lgkmcnt(1)
	v_mfma_f32_32x32x16_bf16 v[32:47], v[2:5], v[6:9], v[32:47]
	v_sub_f32_e32 v2, v92, v209
	v_exp_f32_e32 v91, v2
	v_sub_f32_e32 v2, v93, v209
	v_exp_f32_e32 v92, v2
	v_sub_f32_e32 v2, v94, v209
	v_exp_f32_e32 v93, v2
	ds_read_b128 v[2:5], v247 offset:96
	s_waitcnt lgkmcnt(1)
	v_mfma_f32_32x32x16_bf16 v[16:31], v[10:13], v[6:9], v[16:31]
	ds_read_b128 v[10:13], v247 offset:4704
	v_sub_f32_e32 v6, v95, v209
	v_exp_f32_e32 v94, v6
	v_add_f32_e32 v0, v106, v14
	v_add_f32_e32 v0, v107, v0
	v_cvt_pk_bf16_f32 v6, v87, v88
	v_cvt_pk_bf16_f32 v7, v89, v90
	v_cvt_pk_bf16_f32 v8, v91, v92
	v_cvt_pk_bf16_f32 v9, v93, v94
	v_add_f32_e32 v0, v108, v0
	v_add_f32_e32 v0, v15, v0
	s_waitcnt lgkmcnt(1)
	v_mfma_f32_32x32x16_bf16 v[64:79], v[2:5], v[6:9], v[64:79]
	ds_read_b128 v[2:5], v247 offset:9312
	v_add_f32_e32 v0, v80, v0
	v_add_f32_e32 v0, v81, v0
	v_add_f32_e32 v0, v82, v0
	v_add_f32_e32 v0, v83, v0
	v_add_f32_e32 v0, v84, v0
	v_add_f32_e32 v0, v85, v0
	s_waitcnt lgkmcnt(1)
	v_mfma_f32_32x32x16_bf16 v[48:63], v[10:13], v[6:9], v[48:63]
	ds_read_b128 v[10:13], v247 offset:13920
	v_add_f32_e32 v0, v86, v0
	v_add_f32_e32 v0, v87, v0
	v_add_f32_e32 v0, v88, v0
	v_add_f32_e32 v0, v89, v0
	v_add_f32_e32 v0, v90, v0
	v_add_f32_e32 v0, v91, v0
	s_waitcnt lgkmcnt(1)
	v_mfma_f32_32x32x16_bf16 v[32:47], v[2:5], v[6:9], v[32:47]
	v_add_f32_e32 v0, v92, v0
	v_add_f32_e32 v0, v93, v0
	v_add_f32_e32 v0, v94, v0
	v_add_f32_e32 v205, v205, v0
	s_waitcnt lgkmcnt(0)
	v_mfma_f32_32x32x16_bf16 v[16:31], v[10:13], v[6:9], v[16:31]
.LBB0_1261:
	s_or_b64 exec, exec, s[10:11]
	s_add_i32 s43, s43, 64
	s_mov_b32 s8, 0x1a000
	s_sub_i32 s10, 0, s8
	s_bitcmp1_b32 s44, 0
	s_cselect_b32 s8, s8, s10
	v_add_u32_e32 v241, s8, v241
	v_subrev_u32_e32 v236, s8, v236
	v_subrev_u32_e32 v237, s8, v237
	v_subrev_u32_e32 v238, s8, v238
	s_mov_b32 s8, 0x4800
	s_sub_i32 s10, 0, s8
	s_bitcmp1_b32 s44, 0
	s_cselect_b32 s8, s8, s10
	v_add_u32_e32 v247, s8, v247
	v_subrev_u32_e32 v245, s8, v245
	v_subrev_u32_e32 v246, s8, v246
	s_waitcnt lgkmcnt(0)
	s_barrier
	s_cmp_eq_u32 s42, s44
	s_cbranch_scc0 .LBB0_1262
	v_subrev_u32_e32 v236, 0x1a000, v236
	v_subrev_u32_e32 v237, 0x1a000, v237
	v_subrev_u32_e32 v238, 0x1a000, v238
	v_subrev_u32_e32 v245, 0x4800, v245
	v_subrev_u32_e32 v246, 0x4800, v246
	s_branch .LBB0_1270
.LBB0_1262:
	s_add_i32 s44, s44, 1
	s_cmp_ge_u32 s44, s42
	s_cbranch_scc1 .LBB0_1264
	s_waitcnt vmcnt(0)
	ds_write_b128 v236, v[172:175]
	ds_write_b128 v237, v[168:171]
	ds_write_b128 v238, v[176:179]
	ds_write2_b64 v245, v[160:161], v[162:163] offset1:2
	ds_write2_b64 v246, v[164:165], v[166:167] offset1:2
	s_add_i32 s8, s44, 1
	s_cmp_ge_u32 s8, s42
	s_cbranch_scc1 .LBB0_1264
	s_add_i32 s8, s43, 128
	s_mul_i32 s10, s8, 0x180
	s_mul_hi_u32 s11, s8, 0x180
	s_add_u32 s10, s0, s10
	s_addc_u32 s11, s1, s11
	v_lshl_add_u64 v[2:3], v[186:187], 1, s[10:11]
	v_lshl_add_u64 v[4:5], v[188:189], 1, s[10:11]
	global_load_dwordx4 v[172:175], v[2:3], off
	global_load_dwordx4 v[168:171], v[4:5], off
	v_lshl_add_u64 v[2:3], v[190:191], 1, s[10:11]
	s_lshl_b64 s[10:11], s[8:9], 1
	v_lshl_add_u64 v[4:5], v[210:211], 0, s[10:11]
	global_load_dwordx4 v[176:179], v[2:3], off
	global_load_dwordx4 v[160:163], v[4:5], off
	v_lshl_add_u64 v[2:3], v[212:213], 0, s[10:11]
	global_load_dwordx4 v[164:167], v[2:3], off

.LBB0_1271:
	v_lshl_add_u64 v[28:29], v[2:3], 0, s[10:11]
	v_add_co_u32_e64 v38, s[0:1], s36, v28
	v_add_co_u32_e32 v36, vcc, 0xc000000, v28
	s_nop 0
	v_addc_co_u32_e64 v39, s[0:1], 0, v29, s[0:1]
	v_add_co_u32_e64 v40, s[0:1], s37, v28
	v_addc_co_u32_e32 v37, vcc, 0, v29, vcc
	s_nop 0
	v_addc_co_u32_e64 v41, s[0:1], 0, v29, s[0:1]
	v_add_co_u32_e64 v42, s[0:1], s38, v28
	ds_read_b128 v[4:7], v0
	ds_read_b128 v[8:11], v0 offset:1088
	ds_read_b128 v[12:15], v0 offset:2176
	ds_read_b128 v[16:19], v0 offset:3264
	v_addc_co_u32_e64 v43, s[0:1], 0, v29, s[0:1]
	global_load_dwordx4 v[20:23], v[40:41], off
	global_load_dwordx4 v[24:27], v[42:43], off
	global_load_dwordx4 v[28:31], v[36:37], off
	global_load_dwordx4 v[32:35], v[38:39], off
	s_add_u32 s10, s10, 0x10000
	s_waitcnt lgkmcnt(1)
	v_lshlrev_b32_e32 v52, 16, v12
	v_and_b32_e32 v53, 0xffff0000, v12
	v_lshlrev_b32_e32 v12, 16, v13
	v_and_b32_e32 v13, 0xffff0000, v13
	v_lshlrev_b32_e32 v54, 16, v14
	v_and_b32_e32 v55, 0xffff0000, v14
	v_lshlrev_b32_e32 v14, 16, v15
	v_and_b32_e32 v15, 0xffff0000, v15
	s_addc_u32 s11, s11, 0
	v_lshlrev_b32_e32 v44, 16, v4
	v_and_b32_e32 v45, 0xffff0000, v4
	v_lshlrev_b32_e32 v4, 16, v5
	v_and_b32_e32 v5, 0xffff0000, v5
	v_lshlrev_b32_e32 v46, 16, v6
	v_and_b32_e32 v47, 0xffff0000, v6
	v_lshlrev_b32_e32 v6, 16, v7
	v_and_b32_e32 v7, 0xffff0000, v7
	v_lshlrev_b32_e32 v48, 16, v8
	v_and_b32_e32 v49, 0xffff0000, v8
	v_lshlrev_b32_e32 v8, 16, v9
	v_and_b32_e32 v9, 0xffff0000, v9
	v_lshlrev_b32_e32 v50, 16, v10
	v_and_b32_e32 v51, 0xffff0000, v10
	v_lshlrev_b32_e32 v10, 16, v11
	v_and_b32_e32 v11, 0xffff0000, v11
	s_waitcnt lgkmcnt(0)
	v_lshlrev_b32_e32 v56, 16, v16
	v_and_b32_e32 v57, 0xffff0000, v16
	v_lshlrev_b32_e32 v16, 16, v17
	v_and_b32_e32 v17, 0xffff0000, v17
	v_lshlrev_b32_e32 v58, 16, v18
	v_and_b32_e32 v59, 0xffff0000, v18
	v_lshlrev_b32_e32 v18, 16, v19
	v_and_b32_e32 v19, 0xffff0000, v19
	v_add_u32_e32 v0, 0x1100, v0
	s_cmp_eq_u32 s10, 0x20000
	s_waitcnt vmcnt(3)
	v_lshlrev_b32_e32 v60, 16, v20
	v_and_b32_e32 v61, 0xffff0000, v20
	v_lshlrev_b32_e32 v20, 16, v21
	v_and_b32_e32 v21, 0xffff0000, v21
	v_lshlrev_b32_e32 v62, 16, v22
	v_and_b32_e32 v63, 0xffff0000, v22
	v_lshlrev_b32_e32 v22, 16, v23
	v_and_b32_e32 v23, 0xffff0000, v23
	s_waitcnt vmcnt(2)
	v_lshlrev_b32_e32 v64, 16, v24
	v_and_b32_e32 v65, 0xffff0000, v24
	v_lshlrev_b32_e32 v24, 16, v25
	v_and_b32_e32 v25, 0xffff0000, v25
	v_lshlrev_b32_e32 v66, 16, v26
	v_and_b32_e32 v67, 0xffff0000, v26
	v_lshlrev_b32_e32 v26, 16, v27
	v_and_b32_e32 v27, 0xffff0000, v27
	s_waitcnt vmcnt(1)
	v_lshlrev_b32_e32 v68, 16, v28
	v_and_b32_e32 v69, 0xffff0000, v28
	v_lshlrev_b32_e32 v28, 16, v29
	v_and_b32_e32 v29, 0xffff0000, v29
	v_lshlrev_b32_e32 v70, 16, v30
	v_and_b32_e32 v71, 0xffff0000, v30
	v_lshlrev_b32_e32 v30, 16, v31
	v_and_b32_e32 v31, 0xffff0000, v31
	s_waitcnt vmcnt(0)
	v_lshlrev_b32_e32 v72, 16, v32
	v_and_b32_e32 v73, 0xffff0000, v32
	v_lshlrev_b32_e32 v32, 16, v33
	v_and_b32_e32 v33, 0xffff0000, v33
	v_lshlrev_b32_e32 v74, 16, v34
	v_and_b32_e32 v75, 0xffff0000, v34
	v_lshlrev_b32_e32 v34, 16, v35
	v_and_b32_e32 v35, 0xffff0000, v35
	v_pk_mul_f32 v[52:53], v[52:53], v[60:61]
	v_pk_mul_f32 v[12:13], v[12:13], v[20:21]
	v_pk_mul_f32 v[20:21], v[54:55], v[62:63]
	v_pk_mul_f32 v[14:15], v[14:15], v[22:23]
	v_pk_mul_f32 v[22:23], v[56:57], v[64:65]
	v_pk_mul_f32 v[16:17], v[16:17], v[24:25]
	v_pk_mul_f32 v[24:25], v[58:59], v[66:67]
	v_pk_mul_f32 v[18:19], v[18:19], v[26:27]
	v_pk_mul_f32 v[26:27], v[44:45], v[68:69]
	v_pk_mul_f32 v[28:29], v[4:5], v[28:29]
	v_pk_mul_f32 v[44:45], v[46:47], v[70:71]
	v_pk_mul_f32 v[30:31], v[6:7], v[30:31]
	v_pk_mul_f32 v[46:47], v[48:49], v[72:73]
	v_pk_mul_f32 v[32:33], v[8:9], v[32:33]
	v_pk_mul_f32 v[48:49], v[50:51], v[74:75]
	v_pk_mul_f32 v[34:35], v[10:11], v[34:35]
	v_cvt_pk_bf16_f32 v4, v52, v53
	v_cvt_pk_bf16_f32 v5, v12, v13
	v_cvt_pk_bf16_f32 v6, v20, v21
	v_cvt_pk_bf16_f32 v7, v14, v15
	v_cvt_pk_bf16_f32 v8, v22, v23
	v_cvt_pk_bf16_f32 v9, v16, v17
	v_cvt_pk_bf16_f32 v10, v24, v25
	v_cvt_pk_bf16_f32 v11, v18, v19
	v_cvt_pk_bf16_f32 v12, v26, v27
	v_cvt_pk_bf16_f32 v13, v28, v29
	v_cvt_pk_bf16_f32 v14, v44, v45
	v_cvt_pk_bf16_f32 v15, v30, v31
	v_cvt_pk_bf16_f32 v16, v46, v47
	v_cvt_pk_bf16_f32 v17, v32, v33
	v_cvt_pk_bf16_f32 v18, v48, v49
	v_cvt_pk_bf16_f32 v19, v34, v35
	global_store_dwordx4 v[40:41], v[4:7], off sc1
	global_store_dwordx4 v[42:43], v[8:11], off sc1
	global_store_dwordx4 v[36:37], v[12:15], off sc1
	global_store_dwordx4 v[38:39], v[16:19], off sc1
	s_cbranch_scc0 .LBB0_1271
	s_add_i32 s1, s39, 1
	s_bitcmp0_b32 s39, 0
	s_cselect_b32 s0, s17, s2
	s_mul_i32 s8, s1, s82
	s_add_i32 s0, s0, s8
	s_cmpk_gt_i32 s0, 0x3ff
	s_mov_b32 s39, s1
	s_barrier
	s_cbranch_scc0 .LBB0_1258

.LBB0_1394:
	ds_write_b128 v23, v[4:7]
	s_waitcnt lgkmcnt(0)
	s_barrier
	s_waitcnt vmcnt(0)
	ds_read2st64_b32 v[0:1], v18 offset1:1
	ds_read2st64_b32 v[2:3], v18 offset0:2 offset1:3
	ds_read2st64_b32 v[4:5], v18 offset0:4 offset1:5
	ds_read2st64_b32 v[6:7], v18 offset0:6 offset1:7
	v_lshl_add_u64 v[26:27], s[8:9], 1, v[12:13]
	s_waitcnt lgkmcnt(3)
	v_cvt_pk_bf16_f32 v0, v0, v1
	s_waitcnt lgkmcnt(2)
	v_cvt_pk_bf16_f32 v1, v2, v3
	s_waitcnt lgkmcnt(1)
	v_cvt_pk_bf16_f32 v2, v4, v5
	v_or_b32_e32 v4, s18, v8
	v_ashrrev_i32_e32 v5, 31, v4
	s_waitcnt lgkmcnt(0)
	v_cvt_pk_bf16_f32 v3, v6, v7
	v_lshlrev_b64 v[4:5], 11, v[4:5]
	ds_read2st64_b32 v[6:7], v24 offset1:1
	ds_read2st64_b32 v[28:29], v24 offset0:2 offset1:3
	ds_read2st64_b32 v[30:31], v24 offset0:4 offset1:5
	ds_read2st64_b32 v[32:33], v24 offset0:6 offset1:7
	v_lshl_add_u64 v[4:5], v[26:27], 0, v[4:5]
	global_store_dwordx4 v[4:5], v[0:3], off sc1
	v_add_u32_e32 v4, s18, v20
	v_ashrrev_i32_e32 v5, 31, v4
	v_lshlrev_b64 v[4:5], 11, v[4:5]
	s_add_i32 s17, s17, s82
	s_add_i32 s3, s3, s14
	s_waitcnt lgkmcnt(3)
	v_cvt_pk_bf16_f32 v0, v6, v7
	s_waitcnt lgkmcnt(2)
	v_cvt_pk_bf16_f32 v1, v28, v29
	s_waitcnt lgkmcnt(1)
	v_cvt_pk_bf16_f32 v2, v30, v31
	s_waitcnt lgkmcnt(0)
	v_cvt_pk_bf16_f32 v3, v32, v33
	v_lshl_add_u64 v[4:5], v[26:27], 0, v[4:5]
	s_cmpk_lt_i32 s17, 0x300
	v_add_u32_e32 v25, s15, v25
	global_store_dwordx4 v[4:5], v[0:3], off sc1
	s_cbranch_scc0 .LBB0_1413

.LBB0_1415:
	s_waitcnt vmcnt(1)
	ds_write_b128 v18, v[4:7]
	s_waitcnt vmcnt(0)
	ds_write_b128 v19, v[0:3]
	s_waitcnt lgkmcnt(0)
	s_barrier
	ds_read2st64_b32 v[0:1], v15 offset1:1
	ds_read2st64_b32 v[2:3], v15 offset0:2 offset1:3
	ds_read2st64_b32 v[4:5], v15 offset0:4 offset1:5
	ds_read2st64_b32 v[6:7], v15 offset0:6 offset1:7
	s_add_i32 s0, s3, s6
	s_waitcnt lgkmcnt(3)
	v_cvt_pk_bf16_f32 v0, v0, v1
	s_waitcnt lgkmcnt(2)
	v_cvt_pk_bf16_f32 v1, v2, v3
	s_waitcnt lgkmcnt(1)
	v_cvt_pk_bf16_f32 v2, v4, v5
	v_or_b32_e32 v4, s5, v8
	s_ashr_i32 s1, s0, 31
	v_ashrrev_i32_e32 v5, 31, v4
	v_lshl_add_u64 v[22:23], s[0:1], 1, v[12:13]
	s_waitcnt lgkmcnt(0)
	v_cvt_pk_bf16_f32 v3, v6, v7
	v_lshlrev_b64 v[4:5], 12, v[4:5]
	ds_read2st64_b32 v[6:7], v20 offset1:1
	ds_read2st64_b32 v[24:25], v20 offset0:2 offset1:3
	ds_read2st64_b32 v[26:27], v20 offset0:4 offset1:5
	ds_read2st64_b32 v[28:29], v20 offset0:6 offset1:7
	v_lshl_add_u64 v[4:5], v[22:23], 0, v[4:5]
	global_store_dwordx4 v[4:5], v[0:3], off sc1
	v_add_u32_e32 v4, s5, v16
	v_ashrrev_i32_e32 v5, 31, v4
	v_lshlrev_b64 v[4:5], 12, v[4:5]
	s_add_i32 s9, s9, s82
	s_add_i32 s3, s3, s8
	s_waitcnt lgkmcnt(3)
	v_cvt_pk_bf16_f32 v0, v6, v7
	s_waitcnt lgkmcnt(2)
	v_cvt_pk_bf16_f32 v1, v24, v25
	s_waitcnt lgkmcnt(1)
	v_cvt_pk_bf16_f32 v2, v26, v27
	s_waitcnt lgkmcnt(0)
	v_cvt_pk_bf16_f32 v3, v28, v29
	v_lshl_add_u64 v[4:5], v[22:23], 0, v[4:5]
	s_cmpk_lt_i32 s9, 0x100
	global_store_dwordx4 v[4:5], v[0:3], off sc1
	s_cbranch_scc0 .LBB0_1420

.LBB0_1504:
	v_lshl_add_u64 v[20:21], v[0:1], 0, s[44:45]
	v_add_co_u32_e32 v22, vcc, 0x6000000, v20
	ds_read_b128 v[4:7], v2
	ds_read_b128 v[8:11], v2 offset:2304
	ds_read_b128 v[12:15], v2 offset:4608
	ds_read_b128 v[16:19], v2 offset:6912
	v_addc_co_u32_e32 v23, vcc, 0, v21, vcc
	v_add_co_u32_e32 v24, vcc, 0x6010000, v20
	s_add_u32 s44, s44, 0x40000
	s_nop 0
	v_addc_co_u32_e32 v25, vcc, 0, v21, vcc
	v_add_co_u32_e32 v26, vcc, 0x6020000, v20
	s_addc_u32 s45, s45, 0
	s_nop 0
	v_addc_co_u32_e32 v27, vcc, 0, v21, vcc
	v_add_co_u32_e32 v20, vcc, 0x6030000, v20
	v_add_u32_e32 v2, 0x2400, v2
	s_cmp_lg_u32 s44, 0x80000
	v_addc_co_u32_e32 v21, vcc, 0, v21, vcc
	s_waitcnt lgkmcnt(3)
	global_store_dwordx4 v[22:23], v[4:7], off sc1
	s_waitcnt lgkmcnt(2)
	global_store_dwordx4 v[24:25], v[8:11], off sc1
	s_waitcnt lgkmcnt(1)
	global_store_dwordx4 v[26:27], v[12:15], off sc1
	s_waitcnt lgkmcnt(0)
	global_store_dwordx4 v[20:21], v[16:19], off sc1
	s_cbranch_scc1 .LBB0_1504
	s_waitcnt lgkmcnt(0)
	s_branch .LBB0_1487

.LBB0_1576:
	v_lshl_add_u64 v[18:19], v[168:169], 0, s[14:15]
	v_add_co_u32_e32 v20, vcc, 0x6000000, v18
	ds_read_b128 v[2:5], v0
	ds_read_b128 v[6:9], v0 offset:1152
	ds_read_b128 v[10:13], v0 offset:2304
	ds_read_b128 v[14:17], v0 offset:3456
	v_addc_co_u32_e32 v21, vcc, 0, v19, vcc
	v_add_co_u32_e32 v22, vcc, 0x6008000, v18
	s_add_u32 s14, s14, 0x20000
	s_nop 0
	v_addc_co_u32_e32 v23, vcc, 0, v19, vcc
	v_add_co_u32_e32 v24, vcc, 0x6010000, v18
	s_addc_u32 s15, s15, 0
	s_nop 0
	v_addc_co_u32_e32 v25, vcc, 0, v19, vcc
	v_add_co_u32_e32 v18, vcc, 0x6018000, v18
	v_add_u32_e32 v0, 0x1200, v0
	s_cmp_lg_u32 s14, 0x40000
	v_addc_co_u32_e32 v19, vcc, 0, v19, vcc
	s_waitcnt lgkmcnt(3)
	global_store_dwordx4 v[20:21], v[2:5], off sc1
	s_waitcnt lgkmcnt(2)
	global_store_dwordx4 v[22:23], v[6:9], off sc1
	s_waitcnt lgkmcnt(1)
	global_store_dwordx4 v[24:25], v[10:13], off sc1
	s_waitcnt lgkmcnt(0)
	global_store_dwordx4 v[18:19], v[14:17], off sc1
	s_cbranch_scc1 .LBB0_1576
	s_waitcnt lgkmcnt(0)
	s_add_i32 s26, s26, s82
	s_add_i32 s23, s23, s82
	s_cmpk_lt_i32 s26, 0x400
	s_cbranch_scc1 .LBB0_1563

.LBB0_1700:
	v_add_u32_e32 v17, s17, v72
	v_cmp_gt_i32_e64 s[6:7], s16, v17
	v_lshrrev_b32_e32 v83, 3, v72
	v_and_b32_e32 v73, 0x700, v80
	v_cndmask_b32_e64 v16, v72, v17, s[6:7]
	v_lshlrev_b32_e32 v18, 5, v16
	v_lshrrev_b32_e32 v19, 3, v16
	v_and_b32_e32 v18, 0x700, v18
	v_and_b32_e32 v19, 0xf8, v19
	v_and_b32_e32 v20, 0xfffff807, v16
	v_or3_b32 v18, v18, v20, v19
	v_cndmask_b32_e32 v16, v16, v18, vcc
	v_add_u32_e32 v18, s17, v17
	v_cmp_gt_i32_e64 s[4:5], s16, v18
	v_add_u32_e32 v82, s17, v18
	v_cmp_gt_i32_e64 s[0:1], s16, v82
	v_cndmask_b32_e64 v19, v72, v18, s[4:5]
	v_lshlrev_b32_e32 v17, 5, v19
	v_and_b32_e32 v20, 0x700, v17
	v_ashrrev_i32_e32 v17, 31, v16
	v_lshlrev_b64 v[16:17], 12, v[16:17]
	v_lshl_add_u64 v[70:71], v[64:65], 0, v[16:17]
	v_lshrrev_b32_e32 v16, 3, v19
	v_and_b32_e32 v16, 0xf8, v16
	v_and_b32_e32 v17, 0xfffff807, v19
	v_or3_b32 v16, v20, v17, v16
	v_cndmask_b32_e32 v16, v19, v16, vcc
	v_ashrrev_i32_e32 v17, 31, v16
	v_lshlrev_b64 v[16:17], 12, v[16:17]
	global_load_dwordx4 v[60:63], v[70:71], off
	global_load_dwordx4 v[56:59], v[70:71], off offset:1024
	v_lshl_add_u64 v[68:69], v[64:65], 0, v[16:17]
	v_cndmask_b32_e64 v16, v72, v82, s[0:1]
	global_load_dwordx4 v[52:55], v[70:71], off offset:2048
	v_lshlrev_b32_e32 v17, 5, v16
	v_lshrrev_b32_e32 v18, 3, v16
	global_load_dwordx4 v[48:51], v[70:71], off offset:3072
	v_and_b32_e32 v19, 0xfffff807, v16
	v_and_b32_e32 v17, 0x700, v17
	v_and_b32_e32 v18, 0xf8, v18
	v_or3_b32 v17, v17, v19, v18
	v_cndmask_b32_e32 v16, v16, v17, vcc
	v_ashrrev_i32_e32 v17, 31, v16
	global_load_dwordx4 v[44:47], v[68:69], off
	global_load_dwordx4 v[40:43], v[68:69], off offset:1024
	global_load_dwordx4 v[36:39], v[68:69], off offset:2048
	global_load_dwordx4 v[32:35], v[68:69], off offset:3072
	v_lshlrev_b64 v[16:17], 12, v[16:17]
	v_lshl_add_u64 v[66:67], v[64:65], 0, v[16:17]
	global_load_dwordx4 v[28:31], v[66:67], off
	global_load_dwordx4 v[24:27], v[66:67], off offset:1024
	global_load_dwordx4 v[20:23], v[66:67], off offset:2048
	global_load_dwordx4 v[16:19], v[66:67], off offset:3072
	s_waitcnt lgkmcnt(0)
	v_and_b32_e32 v84, 0xfffff807, v72
	v_and_b32_e32 v83, 0xf8, v83
	v_or3_b32 v73, v73, v84, v83
	v_cndmask_b32_e32 v72, v72, v73, vcc
	v_ashrrev_i32_e32 v73, 31, v72
	v_lshlrev_b64 v[72:73], 12, v[72:73]
	v_lshl_add_u64 v[72:73], v[64:65], 0, v[72:73]
	global_load_dwordx4 v[90:93], v[72:73], off
	global_load_dwordx4 v[94:97], v[72:73], off offset:1024
	global_load_dwordx4 v[98:101], v[72:73], off offset:2048
	global_load_dwordx4 v[102:105], v[72:73], off offset:3072
	s_waitcnt vmcnt(15)
	v_pk_mul_f32 v[84:85], v[60:61], v[60:61]
	s_waitcnt vmcnt(14)
	v_pk_mul_f32 v[88:89], v[56:57], v[56:57]
	v_pk_mul_f32 v[86:87], v[62:63], v[62:63]
	v_pk_mul_f32 v[106:107], v[58:59], v[58:59]
	s_waitcnt vmcnt(13)
	v_pk_mul_f32 v[108:109], v[52:53], v[52:53]
	v_add_f32_e32 v83, v88, v89
	v_add_f32_e32 v124, v84, v85
	v_pk_mul_f32 v[110:111], v[54:55], v[54:55]
	s_waitcnt vmcnt(12)
	v_pk_mul_f32 v[112:113], v[48:49], v[48:49]
	v_add_f32_e32 v125, v108, v109
	v_add_f32_e32 v83, v83, v106
	v_add_f32_e32 v86, v124, v86
	v_pk_mul_f32 v[114:115], v[50:51], v[50:51]
	v_add_f32_e32 v126, v112, v113
	s_waitcnt vmcnt(11)
	v_pk_mul_f32 v[84:85], v[44:45], v[44:45]
	v_add_f32_e32 v106, v125, v110
	v_add_f32_e32 v83, v83, v107
	v_add_f32_e32 v86, v86, v87
	v_pk_mul_f32 v[88:89], v[46:47], v[46:47]
	s_waitcnt vmcnt(10)
	v_pk_mul_f32 v[108:109], v[40:41], v[40:41]
	v_add_f32_e32 v110, v126, v114
	v_add_f32_e32 v87, v106, v111
	v_add_f32_e32 v83, v86, v83
	v_add_f32_e32 v84, v84, v85
	v_pk_mul_f32 v[112:113], v[42:43], v[42:43]
	s_waitcnt vmcnt(9)
	v_pk_mul_f32 v[116:117], v[36:37], v[36:37]
	v_add_f32_e32 v108, v108, v109
	v_add_f32_e32 v106, v110, v115
	v_add_f32_e32 v83, v83, v87
	v_add_f32_e32 v84, v84, v88
	v_pk_mul_f32 v[118:119], v[38:39], v[38:39]
	v_add_f32_e32 v83, v83, v106
	v_add_f32_e32 v86, v108, v112
	v_add_f32_e32 v84, v84, v89
	v_add_f32_e32 v85, v116, v117
	s_waitcnt vmcnt(6)
	v_pk_mul_f32 v[88:89], v[24:25], v[24:25]
	v_add_f32_e32 v86, v86, v113
	v_add_f32_e32 v85, v85, v118
	v_add_f32_e32 v88, v88, v89
	ds_bpermute_b32 v89, v74, v83
	v_pk_mul_f32 v[120:121], v[32:33], v[32:33]
	v_add_f32_e32 v84, v84, v86
	v_add_f32_e32 v85, v85, v119
	v_pk_mul_f32 v[122:123], v[34:35], v[34:35]
	v_add_f32_e32 v84, v84, v85
	v_add_f32_e32 v85, v120, v121
	v_add_f32_e32 v85, v85, v122
	v_add_f32_e32 v85, v85, v123
	v_add_f32_e32 v116, v84, v85
	v_pk_mul_f32 v[84:85], v[28:29], v[28:29]
	s_waitcnt lgkmcnt(0)
	v_add_f32_e32 v83, v83, v89
	v_add_f32_e32 v84, v84, v85
	ds_bpermute_b32 v85, v75, v83
	v_pk_mul_f32 v[86:87], v[30:31], v[30:31]
	v_pk_mul_f32 v[106:107], v[26:27], v[26:27]
	s_waitcnt vmcnt(5)
	v_pk_mul_f32 v[108:109], v[20:21], v[20:21]
	v_pk_mul_f32 v[110:111], v[22:23], v[22:23]
	s_waitcnt lgkmcnt(0)
	v_add_f32_e32 v83, v83, v85
	v_add_f32_e32 v88, v88, v106
	v_add_f32_e32 v84, v84, v86
	v_add_f32_e32 v86, v108, v109
	ds_bpermute_b32 v85, v76, v83
	v_add_f32_e32 v88, v88, v107
	v_add_f32_e32 v84, v84, v87
	v_add_f32_e32 v86, v86, v110
	s_waitcnt vmcnt(4)
	v_pk_mul_f32 v[112:113], v[16:17], v[16:17]
	v_add_f32_e32 v84, v84, v88
	v_add_f32_e32 v86, v86, v111
	v_pk_mul_f32 v[114:115], v[18:19], v[18:19]
	v_add_f32_e32 v108, v84, v86
	v_add_f32_e32 v84, v112, v113
	v_add_f32_e32 v84, v84, v114
	s_waitcnt vmcnt(3)
	v_mov_b32_e32 v86, v91
	s_waitcnt vmcnt(2)
	v_mov_b32_e32 v87, v95
	v_add_f32_e32 v109, v84, v115
	s_waitcnt lgkmcnt(0)
	v_add_f32_e32 v83, v83, v85
	v_mov_b32_e32 v84, v90
	v_mov_b32_e32 v85, v94
	v_pk_mul_f32 v[86:87], v[86:87], v[86:87]
	v_mov_b32_e32 v88, v93
	v_pk_fma_f32 v[84:85], v[84:85], v[84:85], v[86:87]
	v_mov_b32_e32 v86, v92
	v_mov_b32_e32 v87, v96
	v_mov_b32_e32 v89, v97
	v_pk_fma_f32 v[84:85], v[86:87], v[86:87], v[84:85]
	s_waitcnt vmcnt(1)
	v_mov_b32_e32 v86, v98
	v_pk_fma_f32 v[84:85], v[88:89], v[88:89], v[84:85]
	v_mov_b32_e32 v88, v99
	s_waitcnt vmcnt(0)
	v_mov_b32_e32 v89, v103
	v_mov_b32_e32 v87, v102
	v_pk_mul_f32 v[88:89], v[88:89], v[88:89]
	v_mov_b32_e32 v106, v101
	v_pk_fma_f32 v[86:87], v[86:87], v[86:87], v[88:89]
	v_mov_b32_e32 v88, v100
	v_mov_b32_e32 v89, v104
	v_mov_b32_e32 v107, v105
	v_pk_fma_f32 v[86:87], v[88:89], v[88:89], v[86:87]
	v_add_f32_e32 v84, v84, v85
	v_pk_fma_f32 v[86:87], v[106:107], v[106:107], v[86:87]
	ds_bpermute_b32 v110, v77, v83
	v_add_f32_e32 v84, v84, v86
	v_add_f32_e32 v84, v84, v87
	ds_bpermute_b32 v85, v74, v84
	ds_bpermute_b32 v87, v74, v116
	s_waitcnt lgkmcnt(2)
	v_add_f32_e32 v83, v83, v110
	ds_bpermute_b32 v88, v78, v83
	v_add_f32_e32 v86, v108, v109
	s_waitcnt lgkmcnt(2)
	v_add_f32_e32 v84, v84, v85
	ds_bpermute_b32 v85, v75, v84
	s_waitcnt lgkmcnt(2)
	v_add_f32_e32 v89, v116, v87
	s_waitcnt lgkmcnt(1)
	v_add_f32_e32 v87, v83, v88
	ds_bpermute_b32 v83, v74, v86
	ds_bpermute_b32 v106, v75, v89
	s_waitcnt lgkmcnt(2)
	v_add_f32_e32 v84, v84, v85
	ds_bpermute_b32 v85, v76, v84
	s_waitcnt lgkmcnt(2)
	v_add_f32_e32 v83, v86, v83
	s_waitcnt lgkmcnt(1)
	v_add_f32_e32 v88, v89, v106
	ds_bpermute_b32 v86, v75, v83
	s_waitcnt lgkmcnt(1)
	v_add_f32_e32 v84, v84, v85
	ds_bpermute_b32 v85, v77, v84
	ds_bpermute_b32 v89, v76, v88
	s_waitcnt lgkmcnt(2)
	v_add_f32_e32 v83, v83, v86
	ds_bpermute_b32 v86, v76, v83
	s_waitcnt lgkmcnt(2)
	v_add_f32_e32 v84, v84, v85
	ds_bpermute_b32 v85, v78, v84
	s_waitcnt lgkmcnt(2)
	v_add_f32_e32 v88, v88, v89
	ds_bpermute_b32 v89, v77, v88
	s_waitcnt lgkmcnt(2)
	v_add_f32_e32 v83, v83, v86
	ds_bpermute_b32 v86, v77, v83
	s_waitcnt lgkmcnt(2)
	v_add_f32_e32 v84, v84, v85
	ds_bpermute_b32 v107, v79, v84
	s_waitcnt lgkmcnt(2)
	v_add_f32_e32 v89, v88, v89
	ds_bpermute_b32 v106, v78, v89
	s_waitcnt lgkmcnt(2)
	v_add_f32_e32 v83, v83, v86
	ds_bpermute_b32 v88, v79, v87
	s_waitcnt lgkmcnt(2)
	v_add_f32_e32 v84, v84, v107
	v_fmamk_f32 v84, v84, 0x3a800000, v81
	v_mul_f32_e32 v86, 0x4b800000, v84
	v_cmp_gt_f32_e64 s[2:3], s19, v84
	s_waitcnt lgkmcnt(1)
	v_add_f32_e32 v85, v89, v106
	ds_bpermute_b32 v89, v78, v83
	v_cndmask_b32_e64 v84, v84, v86, s[2:3]
	v_rsq_f32_e32 v106, v84
	ds_bpermute_b32 v86, v79, v85
	s_waitcnt lgkmcnt(1)
	v_add_f32_e32 v83, v83, v89
	v_mul_f32_e32 v89, 0x45800000, v106
	v_cndmask_b32_e64 v106, v106, v89, s[2:3]
	v_pk_mul_f32 v[90:91], v[90:91], v[106:107] op_sel_hi:[1,0]
	v_pk_mul_f32 v[92:93], v[92:93], v[106:107] op_sel_hi:[1,0]
	v_pk_mul_f32 v[90:91], v[0:1], v[90:91]
	v_pk_mul_f32 v[92:93], v[2:3], v[92:93]
	global_store_dwordx4 v[72:73], v[90:93], off sc1
	ds_bpermute_b32 v84, v79, v83
	s_nop 0
	v_pk_mul_f32 v[90:91], v[94:95], v[106:107] op_sel_hi:[1,0]
	v_pk_mul_f32 v[92:93], v[96:97], v[106:107] op_sel_hi:[1,0]
	v_pk_mul_f32 v[90:91], v[4:5], v[90:91]
	v_pk_mul_f32 v[92:93], v[6:7], v[92:93]
	global_store_dwordx4 v[72:73], v[90:93], off offset:1024 sc1
	s_nop 1
	v_pk_mul_f32 v[90:91], v[98:99], v[106:107] op_sel_hi:[1,0]
	v_pk_mul_f32 v[92:93], v[100:101], v[106:107] op_sel_hi:[1,0]
	v_pk_mul_f32 v[90:91], v[8:9], v[90:91]
	v_pk_mul_f32 v[92:93], v[10:11], v[92:93]
	global_store_dwordx4 v[72:73], v[90:93], off offset:2048 sc1
	s_nop 1
	v_pk_mul_f32 v[90:91], v[102:103], v[106:107] op_sel_hi:[1,0]
	v_pk_mul_f32 v[92:93], v[104:105], v[106:107] op_sel_hi:[1,0]
	v_pk_mul_f32 v[90:91], v[12:13], v[90:91]
	v_pk_mul_f32 v[92:93], v[14:15], v[92:93]
	global_store_dwordx4 v[72:73], v[90:93], off offset:3072 sc1
	s_and_saveexec_b64 s[14:15], s[6:7]
	s_cbranch_execnz .LBB0_1703
	s_or_b64 exec, exec, s[14:15]
	s_and_saveexec_b64 s[6:7], s[4:5]
	s_cbranch_execnz .LBB0_1704

.LBB0_1703:
	v_add_f32_e32 v72, v87, v88
	v_fmamk_f32 v72, v72, 0x3a800000, v81
	v_mul_f32_e32 v73, 0x4b800000, v72
	v_cmp_gt_f32_e64 s[2:3], s19, v72
	s_nop 1
	v_cndmask_b32_e64 v72, v72, v73, s[2:3]
	v_rsq_f32_e32 v72, v72
	s_nop 0
	v_mul_f32_e32 v73, 0x45800000, v72
	v_cndmask_b32_e64 v72, v72, v73, s[2:3]
	v_pk_mul_f32 v[60:61], v[60:61], v[72:73] op_sel_hi:[1,0]
	v_pk_mul_f32 v[62:63], v[62:63], v[72:73] op_sel_hi:[1,0]
	v_pk_mul_f32 v[56:57], v[56:57], v[72:73] op_sel_hi:[1,0]
	v_pk_mul_f32 v[58:59], v[58:59], v[72:73] op_sel_hi:[1,0]
	v_pk_mul_f32 v[52:53], v[52:53], v[72:73] op_sel_hi:[1,0]
	v_pk_mul_f32 v[54:55], v[54:55], v[72:73] op_sel_hi:[1,0]
	v_pk_mul_f32 v[48:49], v[48:49], v[72:73] op_sel_hi:[1,0]
	v_pk_mul_f32 v[50:51], v[50:51], v[72:73] op_sel_hi:[1,0]
	v_pk_mul_f32 v[60:61], v[0:1], v[60:61]
	v_pk_mul_f32 v[62:63], v[2:3], v[62:63]
	v_pk_mul_f32 v[56:57], v[4:5], v[56:57]
	v_pk_mul_f32 v[58:59], v[6:7], v[58:59]
	v_pk_mul_f32 v[52:53], v[8:9], v[52:53]
	v_pk_mul_f32 v[54:55], v[10:11], v[54:55]
	v_pk_mul_f32 v[48:49], v[12:13], v[48:49]
	v_pk_mul_f32 v[50:51], v[14:15], v[50:51]
	global_store_dwordx4 v[70:71], v[60:63], off sc1
	global_store_dwordx4 v[70:71], v[56:59], off offset:1024 sc1
	global_store_dwordx4 v[70:71], v[52:55], off offset:2048 sc1
	global_store_dwordx4 v[70:71], v[48:51], off offset:3072 sc1
	s_or_b64 exec, exec, s[14:15]
	s_and_saveexec_b64 s[6:7], s[4:5]
	s_cbranch_execz .LBB0_1702
.LBB0_1704:
	s_waitcnt lgkmcnt(1)
	v_add_f32_e32 v48, v85, v86
	v_fmamk_f32 v48, v48, 0x3a800000, v81
	v_mul_f32_e32 v49, 0x4b800000, v48
	v_cmp_gt_f32_e64 s[2:3], s19, v48
	s_nop 1
	v_cndmask_b32_e64 v48, v48, v49, s[2:3]
	v_rsq_f32_e32 v48, v48
	s_nop 0
	v_mul_f32_e32 v49, 0x45800000, v48
	v_cndmask_b32_e64 v48, v48, v49, s[2:3]
	v_pk_mul_f32 v[44:45], v[44:45], v[48:49] op_sel_hi:[1,0]
	v_pk_mul_f32 v[46:47], v[46:47], v[48:49] op_sel_hi:[1,0]
	v_pk_mul_f32 v[40:41], v[40:41], v[48:49] op_sel_hi:[1,0]
	v_pk_mul_f32 v[42:43], v[42:43], v[48:49] op_sel_hi:[1,0]
	v_pk_mul_f32 v[36:37], v[36:37], v[48:49] op_sel_hi:[1,0]
	v_pk_mul_f32 v[38:39], v[38:39], v[48:49] op_sel_hi:[1,0]
	v_pk_mul_f32 v[32:33], v[32:33], v[48:49] op_sel_hi:[1,0]
	v_pk_mul_f32 v[34:35], v[34:35], v[48:49] op_sel_hi:[1,0]
	v_pk_mul_f32 v[44:45], v[0:1], v[44:45]
	v_pk_mul_f32 v[46:47], v[2:3], v[46:47]
	v_pk_mul_f32 v[40:41], v[4:5], v[40:41]
	v_pk_mul_f32 v[42:43], v[6:7], v[42:43]
	v_pk_mul_f32 v[36:37], v[8:9], v[36:37]
	v_pk_mul_f32 v[38:39], v[10:11], v[38:39]
	v_pk_mul_f32 v[32:33], v[12:13], v[32:33]
	v_pk_mul_f32 v[34:35], v[14:15], v[34:35]
	global_store_dwordx4 v[68:69], v[44:47], off sc1
	global_store_dwordx4 v[68:69], v[40:43], off offset:1024 sc1
	global_store_dwordx4 v[68:69], v[36:39], off offset:2048 sc1
	global_store_dwordx4 v[68:69], v[32:35], off offset:3072 sc1
	s_or_b64 exec, exec, s[6:7]
	s_and_saveexec_b64 s[2:3], s[0:1]
	s_cbranch_execz .LBB0_1699
.LBB0_1705:
	s_waitcnt lgkmcnt(0)
	v_add_f32_e32 v32, v83, v84
	v_fmamk_f32 v32, v32, 0x3a800000, v81
	v_mul_f32_e32 v33, 0x4b800000, v32
	v_cmp_gt_f32_e64 s[0:1], s19, v32
	s_nop 1
	v_cndmask_b32_e64 v32, v32, v33, s[0:1]
	v_rsq_f32_e32 v32, v32
	s_nop 0
	v_mul_f32_e32 v33, 0x45800000, v32
	v_cndmask_b32_e64 v32, v32, v33, s[0:1]
	v_pk_mul_f32 v[28:29], v[28:29], v[32:33] op_sel_hi:[1,0]
	v_pk_mul_f32 v[30:31], v[30:31], v[32:33] op_sel_hi:[1,0]
	v_pk_mul_f32 v[24:25], v[24:25], v[32:33] op_sel_hi:[1,0]
	v_pk_mul_f32 v[26:27], v[26:27], v[32:33] op_sel_hi:[1,0]
	v_pk_mul_f32 v[20:21], v[20:21], v[32:33] op_sel_hi:[1,0]
	v_pk_mul_f32 v[22:23], v[22:23], v[32:33] op_sel_hi:[1,0]
	v_pk_mul_f32 v[16:17], v[16:17], v[32:33] op_sel_hi:[1,0]
	v_pk_mul_f32 v[18:19], v[18:19], v[32:33] op_sel_hi:[1,0]
	v_pk_mul_f32 v[28:29], v[0:1], v[28:29]
	v_pk_mul_f32 v[30:31], v[2:3], v[30:31]
	v_pk_mul_f32 v[24:25], v[4:5], v[24:25]
	v_pk_mul_f32 v[26:27], v[6:7], v[26:27]
	v_pk_mul_f32 v[20:21], v[8:9], v[20:21]
	v_pk_mul_f32 v[22:23], v[10:11], v[22:23]
	v_pk_mul_f32 v[16:17], v[12:13], v[16:17]
	v_pk_mul_f32 v[18:19], v[14:15], v[18:19]
	global_store_dwordx4 v[66:67], v[28:31], off sc1
	global_store_dwordx4 v[66:67], v[24:27], off offset:1024 sc1
	global_store_dwordx4 v[66:67], v[20:23], off offset:2048 sc1
	global_store_dwordx4 v[66:67], v[16:19], off offset:3072 sc1
	s_branch .LBB0_1699
